# stack of individually neutral edits on v083: in-proj padding MFMAs skipped, pass2 second load batch kept in flight, FFN13 epilogue row-stat prefetch, final-norm row prefetch, nt on the cast stream
# speedup vs baseline: 1.0105x; 1.0105x over previous
; #define PG8_STAGE(bufoff, gbase, voff) do { _Pragma("unroll") for (int _i = 0; _i < 2; ++_i) \
;         __builtin_amdgcn_global_load_lds((const unsigned*)((const char*)(gbase) + (voff)[_i]), (PG8_LAS unsigned*)(lds + (bufoff) + ldsw + _i * 8192), 16, 0, 0); } while (0)
; #define PG8_LDA(dst, b, h) do { _Pragma("unroll") for (int m = 0; m < 4; ++m) _Pragma("unroll") for (int k = 0; k < 2; ++k) dst[m][k] = *(const PG8_LAS bf16x8*)(lds + PG8_SA(b, h) + aoff + m * 2048 + k * 1024); } while (0)
; #define PG8_LDB(dst, b, h) do { _Pragma("unroll") for (int n = 0; n < 2; ++n) _Pragma("unroll") for (int k = 0; k < 2; ++k) dst[n][k] = *(const PG8_LAS bf16x8*)(lds + PG8_SB(b, h) + boff + n * 2048 + k * 1024); } while (0)
; #define PG8_MMA(ai, bj, At, Bt) do { __builtin_amdgcn_s_setprio(1); _Pragma("unroll") for (int m = 0; m < 4; ++m) _Pragma("unroll") for (int n = 0; n < 2; ++n) _Pragma("unroll") for (int k = 0; k < 2; ++k) \
;         acc[ai][bj][m][n] = __builtin_amdgcn_mfma_f32_16x16x32_bf16(Bt[n][k], At[m][k], acc[ai][bj][m][n], 0, 0, 0); __builtin_amdgcn_s_setprio(0); } while (0)
; #define PG8_WAIT_V(n) asm volatile("s_waitcnt vmcnt(" #n ")" ::: "memory")
; #define PG8_WAIT_L(n) asm volatile("s_waitcnt lgkmcnt(" #n ")" ::: "memory")
; #define PG8_BAR __builtin_amdgcn_s_barrier()
; #define PG8_SCHED __builtin_amdgcn_sched_barrier(0)
; template <class Epi, class Sched, bool ALIGN_EPI = false, bool SP2 = false>
; __device__ __forceinline__ void gemm_phase(PG8_LAS unsigned char* lds, const Gemm g, const Sched& S, const Epi& E) {
;     ...
;             PG8_LDB(B0, 0, 0); PG8_LDB(B1, 0, 1); PG8_SCHED; PG8_LDA(At, 0, 0); PG8_STAGE(PG8_SA(1, 1), a1 + hstepA, voffA);
;             PG8_WAIT_V(8); PG8_WAIT_L(0); PG8_BAR; PG8_MMA(0, 0, At, B0); PG8_MMA(0, 1, At, B1); PG8_BAR; PG8_SCHED;
;             PG8_LDA(At, 0, 1); PG8_STAGE(PG8_SB(0, 0), b2, voffB); PG8_STAGE(PG8_SB(0, 1), b2 + hstepB, voffB); PG8_STAGE(PG8_SA(0, 0), a2, voffA);
;             PG8_WAIT_V(8); PG8_WAIT_L(0); PG8_BAR; PG8_MMA(1, 0, At, B0); PG8_MMA(1, 1, At, B1); PG8_BAR; PG8_SCHED;
.LBB0_201:
	s_add_u32 s28, s26, 0xfff80080
	s_addc_u32 s29, s27, -1
	s_add_i32 s49, 0, 0x10000
	s_cmp_eq_u32 s48, 28
	s_cselect_b32 s31, s21, s29
	s_cselect_b32 s30, s44, s28
	s_cselect_b32 s29, s19, s47
	s_cselect_b32 s28, s45, s46
	s_add_i32 s52, 0, 0x14000
	v_add_u32_e32 v156, s49, v145
	v_add_u32_e32 v172, s52, v145
	ds_read_b128 v[140:143], v156
	ds_read_b128 v[148:151], v156 offset:1024
	ds_read_b128 v[152:155], v156 offset:2048
	ds_read_b128 v[156:159], v156 offset:3072
	ds_read_b128 v[160:163], v172
	ds_read_b128 v[164:167], v172 offset:1024
	ds_read_b128 v[168:171], v172 offset:2048
	ds_read_b128 v[172:175], v172 offset:3072
	v_lshl_add_u64 v[192:193], s[26:27], 0, v[138:139]
	s_add_i32 m0, s35, 0xc000
	ds_read_b128 v[176:179], v147
	ds_read_b128 v[180:183], v147 offset:1024
	ds_read_b128 v[184:187], v147 offset:2048
	ds_read_b128 v[188:191], v147 offset:3072
	ds_read_b128 v[206:209], v147 offset:4096
	ds_read_b128 v[210:213], v147 offset:5120
	ds_read_b128 v[214:217], v147 offset:6144
	ds_read_b128 v[218:221], v147 offset:7168
	global_load_lds_dwordx4 v[192:193], off
	v_lshl_add_u64 v[192:193], s[26:27], 0, v[136:137]
	s_add_i32 m0, s35, 0xe000
	s_nop 0
	global_load_lds_dwordx4 v[192:193], off
	s_waitcnt vmcnt(8)
	s_waitcnt lgkmcnt(0)
	s_barrier
	s_waitcnt lgkmcnt(0)
	v_mfma_f32_16x16x32_bf16 v[126:129], v[140:143], v[176:179], v[126:129]
	v_mfma_f32_16x16x32_bf16 v[122:125], v[152:155], v[176:179], v[122:125]
	v_mfma_f32_16x16x32_bf16 v[108:111], v[140:143], v[184:187], v[108:111]
	v_mfma_f32_16x16x32_bf16 v[104:107], v[152:155], v[184:187], v[104:107]
	v_mfma_f32_16x16x32_bf16 v[92:95], v[140:143], v[206:209], v[92:95]
	v_mfma_f32_16x16x32_bf16 v[88:91], v[152:155], v[206:209], v[88:91]
	v_mfma_f32_16x16x32_bf16 v[76:79], v[140:143], v[214:217], v[76:79]
	v_mfma_f32_16x16x32_bf16 v[72:75], v[152:155], v[214:217], v[72:75]
	v_mfma_f32_16x16x32_bf16 v[126:129], v[148:151], v[180:183], v[126:129]
	v_mfma_f32_16x16x32_bf16 v[122:125], v[156:159], v[180:183], v[122:125]
	v_mfma_f32_16x16x32_bf16 v[108:111], v[148:151], v[188:191], v[108:111]
	v_mfma_f32_16x16x32_bf16 v[104:107], v[156:159], v[188:191], v[104:107]
	v_mfma_f32_16x16x32_bf16 v[92:95], v[148:151], v[210:213], v[92:95]
	v_mfma_f32_16x16x32_bf16 v[88:91], v[156:159], v[210:213], v[88:91]
	v_mfma_f32_16x16x32_bf16 v[76:79], v[148:151], v[218:221], v[76:79]
	v_mfma_f32_16x16x32_bf16 v[72:75], v[156:159], v[218:221], v[72:75]
	s_cmp_eq_u32 s42, 20
	s_cbranch_scc1 .Lat_ipsk0
	v_mfma_f32_16x16x32_bf16 v[118:121], v[160:163], v[176:179], v[118:121]
	v_mfma_f32_16x16x32_bf16 v[114:117], v[168:171], v[176:179], v[114:117]
	v_mfma_f32_16x16x32_bf16 v[100:103], v[160:163], v[184:187], v[100:103]
	v_mfma_f32_16x16x32_bf16 v[96:99], v[168:171], v[184:187], v[96:99]
	v_mfma_f32_16x16x32_bf16 v[84:87], v[160:163], v[206:209], v[84:87]
	v_mfma_f32_16x16x32_bf16 v[80:83], v[168:171], v[206:209], v[80:83]
	v_mfma_f32_16x16x32_bf16 v[68:71], v[160:163], v[214:217], v[68:71]
	v_mfma_f32_16x16x32_bf16 v[64:67], v[168:171], v[214:217], v[64:67]
	v_mfma_f32_16x16x32_bf16 v[118:121], v[164:167], v[180:183], v[118:121]
	v_mfma_f32_16x16x32_bf16 v[114:117], v[172:175], v[180:183], v[114:117]
	v_mfma_f32_16x16x32_bf16 v[100:103], v[164:167], v[188:191], v[100:103]
	v_mfma_f32_16x16x32_bf16 v[96:99], v[172:175], v[188:191], v[96:99]
	v_mfma_f32_16x16x32_bf16 v[84:87], v[164:167], v[210:213], v[84:87]
	v_mfma_f32_16x16x32_bf16 v[80:83], v[172:175], v[210:213], v[80:83]
	v_mfma_f32_16x16x32_bf16 v[68:71], v[164:167], v[218:221], v[68:71]
	v_mfma_f32_16x16x32_bf16 v[64:67], v[172:175], v[218:221], v[64:67]
.Lat_ipsk0:
	s_barrier
	s_add_i32 s49, s49, s34
	v_lshl_add_u64 v[192:193], s[28:29], 0, v[112:113]
	s_mov_b32 m0, s49
	ds_read_b128 v[176:179], v147 offset:16384
	ds_read_b128 v[180:183], v147 offset:17408
	ds_read_b128 v[184:187], v147 offset:18432
	ds_read_b128 v[188:191], v147 offset:19456
	ds_read_b128 v[206:209], v147 offset:20480
	ds_read_b128 v[210:213], v147 offset:21504
	ds_read_b128 v[214:217], v147 offset:22528
	ds_read_b128 v[218:221], v147 offset:23552
	global_load_lds_dwordx4 v[192:193], off
	s_add_i32 m0, s49, 0x2000
	s_add_u32 s50, s28, 0x80000
	v_lshl_add_u64 v[196:197], s[28:29], 0, v[130:131]
	s_addc_u32 s51, s29, 0
	s_add_i32 s49, s52, s34
	global_load_lds_dwordx4 v[196:197], off
	v_lshl_add_u64 v[198:199], s[50:51], 0, v[112:113]
	s_mov_b32 m0, s49
	v_lshl_add_u64 v[202:203], s[30:31], 0, v[132:133]
	global_load_lds_dwordx4 v[198:199], off
	v_lshl_add_u64 v[198:199], s[50:51], 0, v[130:131]
	s_add_i32 m0, s49, 0x2000
	s_nop 0
	global_load_lds_dwordx4 v[198:199], off
	v_lshl_add_u64 v[198:199], s[30:31], 0, v[134:135]
	s_mov_b32 m0, s35
	s_nop 0
	global_load_lds_dwordx4 v[198:199], off
	s_mov_b32 m0, s36
	s_nop 0
	global_load_lds_dwordx4 v[202:203], off
	s_waitcnt vmcnt(8)
	s_waitcnt lgkmcnt(0)
	s_barrier
	s_waitcnt lgkmcnt(0)
	v_mfma_f32_16x16x32_bf16 v[60:63], v[140:143], v[176:179], v[60:63]
	v_mfma_f32_16x16x32_bf16 v[56:59], v[152:155], v[176:179], v[56:59]
	v_mfma_f32_16x16x32_bf16 v[44:47], v[140:143], v[184:187], v[44:47]
	v_mfma_f32_16x16x32_bf16 v[40:43], v[152:155], v[184:187], v[40:43]
	v_mfma_f32_16x16x32_bf16 v[28:31], v[140:143], v[206:209], v[28:31]
	v_mfma_f32_16x16x32_bf16 v[24:27], v[152:155], v[206:209], v[24:27]
	v_mfma_f32_16x16x32_bf16 v[12:15], v[140:143], v[214:217], v[12:15]
	v_mfma_f32_16x16x32_bf16 v[8:11], v[152:155], v[214:217], v[8:11]
	v_mfma_f32_16x16x32_bf16 v[60:63], v[148:151], v[180:183], v[60:63]
	v_mfma_f32_16x16x32_bf16 v[56:59], v[156:159], v[180:183], v[56:59]
	v_mfma_f32_16x16x32_bf16 v[44:47], v[148:151], v[188:191], v[44:47]
	v_mfma_f32_16x16x32_bf16 v[40:43], v[156:159], v[188:191], v[40:43]
	v_mfma_f32_16x16x32_bf16 v[28:31], v[148:151], v[210:213], v[28:31]
	v_mfma_f32_16x16x32_bf16 v[24:27], v[156:159], v[210:213], v[24:27]
	v_mfma_f32_16x16x32_bf16 v[12:15], v[148:151], v[218:221], v[12:15]
	v_mfma_f32_16x16x32_bf16 v[8:11], v[156:159], v[218:221], v[8:11]
	s_cmp_eq_u32 s42, 20
	s_cbranch_scc1 .Lat_ipsk1
; #define PG8_STAGE(bufoff, gbase, voff) do { _Pragma("unroll") for (int _i = 0; _i < 2; ++_i) \
;         __builtin_amdgcn_global_load_lds((const unsigned*)((const char*)(gbase) + (voff)[_i]), (PG8_LAS unsigned*)(lds + (bufoff) + ldsw + _i * 8192), 16, 0, 0); } while (0)
; #define PG8_LDA(dst, b, h) do { _Pragma("unroll") for (int m = 0; m < 4; ++m) _Pragma("unroll") for (int k = 0; k < 2; ++k) dst[m][k] = *(const PG8_LAS bf16x8*)(lds + PG8_SA(b, h) + aoff + m * 2048 + k * 1024); } while (0)
; #define PG8_LDB(dst, b, h) do { _Pragma("unroll") for (int n = 0; n < 2; ++n) _Pragma("unroll") for (int k = 0; k < 2; ++k) dst[n][k] = *(const PG8_LAS bf16x8*)(lds + PG8_SB(b, h) + boff + n * 2048 + k * 1024); } while (0)
; #define PG8_MMA(ai, bj, At, Bt) do { __builtin_amdgcn_s_setprio(1); _Pragma("unroll") for (int m = 0; m < 4; ++m) _Pragma("unroll") for (int n = 0; n < 2; ++n) _Pragma("unroll") for (int k = 0; k < 2; ++k) \
;         acc[ai][bj][m][n] = __builtin_amdgcn_mfma_f32_16x16x32_bf16(Bt[n][k], At[m][k], acc[ai][bj][m][n], 0, 0, 0); __builtin_amdgcn_s_setprio(0); } while (0)
; #define PG8_WAIT_V(n) asm volatile("s_waitcnt vmcnt(" #n ")" ::: "memory")
; #define PG8_WAIT_L(n) asm volatile("s_waitcnt lgkmcnt(" #n ")" ::: "memory")
; #define PG8_BAR __builtin_amdgcn_s_barrier()
; #define PG8_SCHED __builtin_amdgcn_sched_barrier(0)
; template <class Epi, class Sched, bool ALIGN_EPI = false, bool SP2 = false>
; __device__ __forceinline__ void gemm_phase(PG8_LAS unsigned char* lds, const Gemm g, const Sched& S, const Epi& E) {
;     ...
;             PG8_WAIT_V(8); PG8_WAIT_L(0); PG8_BAR; PG8_MMA(1, 0, At, B0); PG8_MMA(1, 1, At, B1); PG8_BAR; PG8_SCHED;
;             PG8_LDB(B0, 1, 0); PG8_LDB(B1, 1, 1); PG8_SCHED; PG8_LDA(At, 1, 0); PG8_STAGE(PG8_SA(0, 1), a2 + hstepA, voffA);
;             PG8_WAIT_V(8); PG8_WAIT_L(0); PG8_BAR; PG8_MMA(0, 0, At, B0); PG8_MMA(0, 1, At, B1); PG8_BAR; PG8_SCHED;
;             PG8_LDA(At, 1, 1); PG8_STAGE(PG8_SB(1, 0), b3, voffB); PG8_STAGE(PG8_SB(1, 1), b3 + hstepB, voffB); PG8_STAGE(PG8_SA(1, 0), a3, voffA);
	v_mfma_f32_16x16x32_bf16 v[52:55], v[160:163], v[176:179], v[52:55]
	v_mfma_f32_16x16x32_bf16 v[48:51], v[168:171], v[176:179], v[48:51]
	v_mfma_f32_16x16x32_bf16 v[36:39], v[160:163], v[184:187], v[36:39]
	v_mfma_f32_16x16x32_bf16 v[32:35], v[168:171], v[184:187], v[32:35]
	v_mfma_f32_16x16x32_bf16 v[20:23], v[160:163], v[206:209], v[20:23]
	v_mfma_f32_16x16x32_bf16 v[16:19], v[168:171], v[206:209], v[16:19]
	v_mfma_f32_16x16x32_bf16 v[4:7], v[160:163], v[214:217], v[4:7]
	v_mfma_f32_16x16x32_bf16 v[0:3], v[168:171], v[214:217], v[0:3]
	v_mfma_f32_16x16x32_bf16 v[52:55], v[164:167], v[180:183], v[52:55]
	v_mfma_f32_16x16x32_bf16 v[48:51], v[172:175], v[180:183], v[48:51]
	v_mfma_f32_16x16x32_bf16 v[36:39], v[164:167], v[188:191], v[36:39]
	v_mfma_f32_16x16x32_bf16 v[32:35], v[172:175], v[188:191], v[32:35]
	v_mfma_f32_16x16x32_bf16 v[20:23], v[164:167], v[210:213], v[20:23]
	v_mfma_f32_16x16x32_bf16 v[16:19], v[172:175], v[210:213], v[16:19]
	v_mfma_f32_16x16x32_bf16 v[4:7], v[164:167], v[218:221], v[4:7]
	v_mfma_f32_16x16x32_bf16 v[0:3], v[172:175], v[218:221], v[0:3]
.Lat_ipsk1:
	s_barrier
	s_add_i32 s49, 0, 0x18000
	s_add_i32 s50, 0, 0x1c000
	v_add_u32_e32 v156, s49, v145
	v_add_u32_e32 v172, s50, v145
	ds_read_b128 v[140:143], v156
	ds_read_b128 v[148:151], v156 offset:1024
	ds_read_b128 v[152:155], v156 offset:2048
	ds_read_b128 v[156:159], v156 offset:3072
	ds_read_b128 v[160:163], v172
	ds_read_b128 v[164:167], v172 offset:1024
	ds_read_b128 v[168:171], v172 offset:2048
	ds_read_b128 v[172:175], v172 offset:3072
	s_add_u32 s30, s30, 0x80000
	s_addc_u32 s31, s31, 0
	s_mov_b32 m0, s37
	v_lshl_add_u64 v[204:205], s[30:31], 0, v[134:135]
	ds_read_b128 v[176:179], v147 offset:32768
	ds_read_b128 v[180:183], v147 offset:33792
	ds_read_b128 v[184:187], v147 offset:34816
	ds_read_b128 v[188:191], v147 offset:35840
	ds_read_b128 v[206:209], v147 offset:36864
	ds_read_b128 v[210:213], v147 offset:37888
	ds_read_b128 v[214:217], v147 offset:38912
	ds_read_b128 v[218:221], v147 offset:39936
	global_load_lds_dwordx4 v[204:205], off
	v_lshl_add_u64 v[204:205], s[30:31], 0, v[132:133]
	s_mov_b32 m0, s38
	s_nop 0
	global_load_lds_dwordx4 v[204:205], off
	s_waitcnt vmcnt(8)
	s_waitcnt lgkmcnt(0)
	s_barrier
	s_waitcnt lgkmcnt(0)
	v_mfma_f32_16x16x32_bf16 v[126:129], v[140:143], v[176:179], v[126:129]
	v_mfma_f32_16x16x32_bf16 v[122:125], v[152:155], v[176:179], v[122:125]
	v_mfma_f32_16x16x32_bf16 v[108:111], v[140:143], v[184:187], v[108:111]
	v_mfma_f32_16x16x32_bf16 v[104:107], v[152:155], v[184:187], v[104:107]
	v_mfma_f32_16x16x32_bf16 v[92:95], v[140:143], v[206:209], v[92:95]
	v_mfma_f32_16x16x32_bf16 v[88:91], v[152:155], v[206:209], v[88:91]
	v_mfma_f32_16x16x32_bf16 v[76:79], v[140:143], v[214:217], v[76:79]
	v_mfma_f32_16x16x32_bf16 v[72:75], v[152:155], v[214:217], v[72:75]
	v_mfma_f32_16x16x32_bf16 v[126:129], v[148:151], v[180:183], v[126:129]
	v_mfma_f32_16x16x32_bf16 v[122:125], v[156:159], v[180:183], v[122:125]
	v_mfma_f32_16x16x32_bf16 v[108:111], v[148:151], v[188:191], v[108:111]
	v_mfma_f32_16x16x32_bf16 v[104:107], v[156:159], v[188:191], v[104:107]
	v_mfma_f32_16x16x32_bf16 v[92:95], v[148:151], v[210:213], v[92:95]
	v_mfma_f32_16x16x32_bf16 v[88:91], v[156:159], v[210:213], v[88:91]
	v_mfma_f32_16x16x32_bf16 v[76:79], v[148:151], v[218:221], v[76:79]
	v_mfma_f32_16x16x32_bf16 v[72:75], v[156:159], v[218:221], v[72:75]
	s_cmp_eq_u32 s42, 20
	s_cbranch_scc1 .Lat_ipsk2
	v_mfma_f32_16x16x32_bf16 v[118:121], v[160:163], v[176:179], v[118:121]
	v_mfma_f32_16x16x32_bf16 v[114:117], v[168:171], v[176:179], v[114:117]
	v_mfma_f32_16x16x32_bf16 v[100:103], v[160:163], v[184:187], v[100:103]
	v_mfma_f32_16x16x32_bf16 v[96:99], v[168:171], v[184:187], v[96:99]
	v_mfma_f32_16x16x32_bf16 v[84:87], v[160:163], v[206:209], v[84:87]
	v_mfma_f32_16x16x32_bf16 v[80:83], v[168:171], v[206:209], v[80:83]
	v_mfma_f32_16x16x32_bf16 v[68:71], v[160:163], v[214:217], v[68:71]
	v_mfma_f32_16x16x32_bf16 v[64:67], v[168:171], v[214:217], v[64:67]
	v_mfma_f32_16x16x32_bf16 v[118:121], v[164:167], v[180:183], v[118:121]
	v_mfma_f32_16x16x32_bf16 v[114:117], v[172:175], v[180:183], v[114:117]
	v_mfma_f32_16x16x32_bf16 v[100:103], v[164:167], v[188:191], v[100:103]
	v_mfma_f32_16x16x32_bf16 v[96:99], v[172:175], v[188:191], v[96:99]
	v_mfma_f32_16x16x32_bf16 v[84:87], v[164:167], v[210:213], v[84:87]
	v_mfma_f32_16x16x32_bf16 v[80:83], v[172:175], v[210:213], v[80:83]
	v_mfma_f32_16x16x32_bf16 v[68:71], v[164:167], v[218:221], v[68:71]
	v_mfma_f32_16x16x32_bf16 v[64:67], v[172:175], v[218:221], v[64:67]
; #define PG8_STAGE(bufoff, gbase, voff) do { _Pragma("unroll") for (int _i = 0; _i < 2; ++_i) \
;         __builtin_amdgcn_global_load_lds((const unsigned*)((const char*)(gbase) + (voff)[_i]), (PG8_LAS unsigned*)(lds + (bufoff) + ldsw + _i * 8192), 16, 0, 0); } while (0)
; #define PG8_LDA(dst, b, h) do { _Pragma("unroll") for (int m = 0; m < 4; ++m) _Pragma("unroll") for (int k = 0; k < 2; ++k) dst[m][k] = *(const PG8_LAS bf16x8*)(lds + PG8_SA(b, h) + aoff + m * 2048 + k * 1024); } while (0)
; #define PG8_MMA(ai, bj, At, Bt) do { __builtin_amdgcn_s_setprio(1); _Pragma("unroll") for (int m = 0; m < 4; ++m) _Pragma("unroll") for (int n = 0; n < 2; ++n) _Pragma("unroll") for (int k = 0; k < 2; ++k) \
;         acc[ai][bj][m][n] = __builtin_amdgcn_mfma_f32_16x16x32_bf16(Bt[n][k], At[m][k], acc[ai][bj][m][n], 0, 0, 0); __builtin_amdgcn_s_setprio(0); } while (0)
; #define PG8_WAIT_V(n) asm volatile("s_waitcnt vmcnt(" #n ")" ::: "memory")
; #define PG8_WAIT_L(n) asm volatile("s_waitcnt lgkmcnt(" #n ")" ::: "memory")
; #define PG8_BAR __builtin_amdgcn_s_barrier()
; #define PG8_SCHED __builtin_amdgcn_sched_barrier(0)
; template <class Epi, class Sched, bool ALIGN_EPI = false, bool SP2 = false>
; __device__ __forceinline__ void gemm_phase(PG8_LAS unsigned char* lds, const Gemm g, const Sched& S, const Epi& E) {
;     ...
;             PG8_WAIT_V(8); PG8_WAIT_L(0); PG8_BAR; PG8_MMA(0, 0, At, B0); PG8_MMA(0, 1, At, B1); PG8_BAR; PG8_SCHED;
;             PG8_LDA(At, 1, 1); PG8_STAGE(PG8_SB(1, 0), b3, voffB); PG8_STAGE(PG8_SB(1, 1), b3 + hstepB, voffB); PG8_STAGE(PG8_SA(1, 0), a3, voffA);
;             PG8_WAIT_V(8); PG8_WAIT_L(0); PG8_BAR; PG8_MMA(1, 0, At, B0); PG8_MMA(1, 1, At, B1); PG8_BAR; PG8_SCHED;
;     ...
;         if constexpr (ALIGN_EPI) { if (wr == 0) PG8_BAR; }
;         if constexpr (!Epi::AFTER_DRAIN) { E(acc, cur, wr, wc, fr, fq); S.done(cur); }
;         if (!has_next) break;
.Lat_ipsk2:
	s_barrier
	s_add_i32 s30, s49, s34
	v_lshl_add_u64 v[192:193], v[192:193], 0, s[2:3]
	s_mov_b32 m0, s30
	ds_read_b128 v[176:179], v147 offset:49152
	ds_read_b128 v[180:183], v147 offset:50176
	ds_read_b128 v[184:187], v147 offset:51200
	ds_read_b128 v[188:191], v147 offset:52224
	ds_read_b128 v[206:209], v147 offset:53248
	ds_read_b128 v[210:213], v147 offset:54272
	ds_read_b128 v[214:217], v147 offset:55296
	ds_read_b128 v[218:221], v147 offset:56320
	global_load_lds_dwordx4 v[192:193], off
	s_add_i32 m0, s30, 0x2000
	s_add_u32 s28, s28, 0x80080
	v_lshl_add_u64 v[192:193], v[196:197], 0, s[2:3]
	s_addc_u32 s29, s29, 0
	s_add_i32 s30, s50, s34
	global_load_lds_dwordx4 v[192:193], off
	v_lshl_add_u64 v[192:193], s[28:29], 0, v[112:113]
	s_mov_b32 m0, s30
	s_nop 0
	global_load_lds_dwordx4 v[192:193], off
	v_lshl_add_u64 v[192:193], s[28:29], 0, v[130:131]
	s_add_i32 m0, s30, 0x2000
	s_nop 0
	global_load_lds_dwordx4 v[192:193], off
	v_lshl_add_u64 v[192:193], v[198:199], 0, s[2:3]
	s_mov_b32 m0, s39
	s_nop 0
	global_load_lds_dwordx4 v[192:193], off
	v_lshl_add_u64 v[192:193], v[202:203], 0, s[2:3]
	s_mov_b32 m0, s40
	s_nop 0
	global_load_lds_dwordx4 v[192:193], off
	s_waitcnt vmcnt(8)
	s_waitcnt lgkmcnt(0)
	s_barrier
	s_waitcnt lgkmcnt(0)
	v_mfma_f32_16x16x32_bf16 v[60:63], v[140:143], v[176:179], v[60:63]
	v_mfma_f32_16x16x32_bf16 v[56:59], v[152:155], v[176:179], v[56:59]
	v_mfma_f32_16x16x32_bf16 v[44:47], v[140:143], v[184:187], v[44:47]
	v_mfma_f32_16x16x32_bf16 v[40:43], v[152:155], v[184:187], v[40:43]
	v_mfma_f32_16x16x32_bf16 v[28:31], v[140:143], v[206:209], v[28:31]
	v_mfma_f32_16x16x32_bf16 v[24:27], v[152:155], v[206:209], v[24:27]
	v_mfma_f32_16x16x32_bf16 v[12:15], v[140:143], v[214:217], v[12:15]
	v_mfma_f32_16x16x32_bf16 v[8:11], v[152:155], v[214:217], v[8:11]
	v_mfma_f32_16x16x32_bf16 v[60:63], v[148:151], v[180:183], v[60:63]
	v_mfma_f32_16x16x32_bf16 v[56:59], v[156:159], v[180:183], v[56:59]
	v_mfma_f32_16x16x32_bf16 v[44:47], v[148:151], v[188:191], v[44:47]
	v_mfma_f32_16x16x32_bf16 v[40:43], v[156:159], v[188:191], v[40:43]
	v_mfma_f32_16x16x32_bf16 v[28:31], v[148:151], v[210:213], v[28:31]
	v_mfma_f32_16x16x32_bf16 v[24:27], v[156:159], v[210:213], v[24:27]
	v_mfma_f32_16x16x32_bf16 v[12:15], v[148:151], v[218:221], v[12:15]
	v_mfma_f32_16x16x32_bf16 v[8:11], v[156:159], v[218:221], v[8:11]
	s_cmp_eq_u32 s42, 20
	s_cbranch_scc1 .Lat_ipsk3
	v_mfma_f32_16x16x32_bf16 v[52:55], v[160:163], v[176:179], v[52:55]
	v_mfma_f32_16x16x32_bf16 v[48:51], v[168:171], v[176:179], v[48:51]
	v_mfma_f32_16x16x32_bf16 v[36:39], v[160:163], v[184:187], v[36:39]
	v_mfma_f32_16x16x32_bf16 v[32:35], v[168:171], v[184:187], v[32:35]
	v_mfma_f32_16x16x32_bf16 v[20:23], v[160:163], v[206:209], v[20:23]
	v_mfma_f32_16x16x32_bf16 v[16:19], v[168:171], v[206:209], v[16:19]
	v_mfma_f32_16x16x32_bf16 v[4:7], v[160:163], v[214:217], v[4:7]
	v_mfma_f32_16x16x32_bf16 v[0:3], v[168:171], v[214:217], v[0:3]
	v_mfma_f32_16x16x32_bf16 v[52:55], v[164:167], v[180:183], v[52:55]
	v_mfma_f32_16x16x32_bf16 v[48:51], v[172:175], v[180:183], v[48:51]
	v_mfma_f32_16x16x32_bf16 v[36:39], v[164:167], v[188:191], v[36:39]
	v_mfma_f32_16x16x32_bf16 v[32:35], v[172:175], v[188:191], v[32:35]
	v_mfma_f32_16x16x32_bf16 v[20:23], v[164:167], v[210:213], v[20:23]
	v_mfma_f32_16x16x32_bf16 v[16:19], v[172:175], v[210:213], v[16:19]
	v_mfma_f32_16x16x32_bf16 v[4:7], v[164:167], v[218:221], v[4:7]
	v_mfma_f32_16x16x32_bf16 v[0:3], v[172:175], v[218:221], v[0:3]
.Lat_ipsk3:
	s_barrier
	s_add_i32 s48, s48, 2
	s_add_u32 s46, s46, 0x100
	s_addc_u32 s47, s47, 0
	s_add_u32 s26, s26, 0x100
	s_addc_u32 s27, s27, 0
	s_cmp_gt_u32 s48, 29
	s_cbranch_scc0 .LBB0_201
	s_and_b64 vcc, exec, s[16:17]
	s_cbranch_vccz .LBB0_204
	s_barrier

; __device__ __forceinline__ void pass2_triple(const KArgs& a, int t) {
;     ...
;     P2_LOAD(uA, dA, 0);
; #pragma unroll 1
;     for (int sb = 0; sb < NCH; sb += 8) {
;         P2_LOAD(uB, dB, sb + 4);
;         P2_STEP(uA, dA, sb);
;         if (sb + 8 < NCH) P2_LOAD(uA, dA, sb + 8);
;         P2_STEP(uB, dB, sb + 4);
.LBB0_342:
	v_mov_b32_e32 v6, v3
	v_and_b32_e32 v5, 0xffff0000, v27
	v_and_b32_e32 v4, 0xffff0000, v25
	v_pk_fma_f32 v[0:1], v[6:7], v[0:1], v[4:5]
	v_and_b32_e32 v3, 0xffff0000, v29
	v_fmac_f32_e32 v3, v11, v2
	v_bfe_u32 v2, v0, 16, 1
	v_add3_u32 v2, v0, v2, s1
	global_store_short_d16_hi v[52:53], v2, off
	v_bfe_u32 v2, v1, 16, 1
	v_add3_u32 v2, v1, v2, s1
	global_store_short_d16_hi v[54:55], v2, off
	v_bfe_u32 v2, v3, 16, 1
	v_add3_u32 v2, v3, v2, s1
	global_store_short_d16_hi v[58:59], v2, off
	v_lshlrev_b32_e32 v2, 16, v88
	v_fmac_f32_e32 v2, v89, v3
	v_bfe_u32 v3, v2, 16, 1
	v_add3_u32 v4, v2, v3, s1
	v_lshlrev_b32_e32 v3, 16, v92
	v_fmac_f32_e32 v3, v2, v93
	v_bfe_u32 v2, v3, 16, 1
	v_lshlrev_b32_e32 v6, 16, v97
	v_add3_u32 v5, v3, v2, s1
	v_fmac_f32_e32 v6, v3, v98
	v_lshlrev_b32_e32 v3, 16, v86
	v_lshlrev_b32_e32 v2, 16, v85
	v_pk_fma_f32 v[0:1], v[30:31], v[0:1], v[2:3]
	v_lshlrev_b32_e32 v3, 16, v90
	v_bfe_u32 v2, v0, 16, 1
	v_add3_u32 v2, v0, v2, s1
	global_store_short_d16_hi v[60:61], v2, off
	v_bfe_u32 v2, v1, 16, 1
	v_add3_u32 v2, v1, v2, s1
	global_store_short_d16_hi v[62:63], v2, off
	v_lshlrev_b32_e32 v2, 16, v87
	v_pk_fma_f32 v[0:1], v[56:57], v[0:1], v[2:3]
	global_store_short_d16_hi v[64:65], v4, off
	v_bfe_u32 v2, v0, 16, 1
	v_add3_u32 v2, v0, v2, s1
	global_store_short_d16_hi v[68:69], v2, off
	v_bfe_u32 v2, v1, 16, 1
	v_add3_u32 v2, v1, v2, s1
	global_store_short_d16_hi v[70:71], v2, off
	v_lshlrev_b32_e32 v3, 16, v94
	v_lshlrev_b32_e32 v2, 16, v91
	v_pk_fma_f32 v[0:1], v[0:1], v[66:67], v[2:3]
	global_store_short_d16_hi v[72:73], v5, off
	v_bfe_u32 v2, v0, 16, 1
	v_add3_u32 v2, v0, v2, s1
	global_store_short_d16_hi v[76:77], v2, off
	v_lshlrev_b32_e32 v3, 16, v96
	v_lshlrev_b32_e32 v2, 16, v95
	v_bfe_u32 v4, v1, 16, 1
	v_pk_fma_f32 v[82:83], v[0:1], v[74:75], v[2:3]
	v_bfe_u32 v0, v6, 16, 1
	v_add3_u32 v4, v1, v4, s1
	v_add3_u32 v0, v6, v0, s1
	v_lshlrev_b32_e32 v101, 16, v99
	global_store_short_d16_hi v[78:79], v4, off
	global_store_short_d16_hi v[80:81], v0, off
	v_fmac_f32_e32 v101, v6, v100
	s_mov_b32 s0, 0x5040100
	s_waitcnt vmcnt(12)
	v_perm_b32 v33, v39, v38, s0
	v_perm_b32 v35, v125, v35, s0
	v_perm_b32 v37, v32, v36, s0
	v_perm_b32 v36, v34, v122, s0
	v_perm_b32 v34, v124, v121, s0
	v_perm_b32 v32, v123, v120, s0
	v_mov_b64_e32 v[24:25], v[32:33]
	v_mov_b64_e32 v[0:1], v[12:13]
	s_add_i32 s16, s16, -8
	s_andn2_b64 vcc, exec, s[14:15]
	s_mov_b32 s17, s18
	v_mov_b64_e32 v[26:27], v[34:35]
	v_mov_b64_e32 v[28:29], v[36:37]
	v_mov_b64_e32 v[2:3], v[14:15]
	v_mov_b64_e32 v[4:5], v[16:17]
	v_mov_b64_e32 v[6:7], v[18:19]
	v_mov_b64_e32 v[8:9], v[20:21]
	v_mov_b64_e32 v[10:11], v[22:23]
	v_mov_b64_e32 v[30:31], v[38:39]
	s_cbranch_vccz .LBB0_340
.LBB0_343:
	s_add_i32 s14, s16, 7
	s_add_i32 s15, s17, 4
	v_mov_b32_e32 v30, s14
	v_mov_b32_e32 v31, s15
	v_cndmask_b32_e64 v112, v30, v31, s[6:7]
	v_cndmask_b32_e64 v56, v30, v31, s[4:5]
	v_cndmask_b32_e64 v60, v30, v31, s[8:9]
	v_lshlrev_b64 v[30:31], 15, v[112:113]
	v_mov_b32_e32 v57, v113
	v_lshl_add_u64 v[52:53], v[40:41], 0, v[30:31]
	v_lshlrev_b64 v[30:31], 9, v[112:113]
	v_lshlrev_b64 v[54:55], 15, v[56:57]
	v_lshlrev_b64 v[56:57], 9, v[56:57]
	v_lshl_add_u64 v[30:31], v[42:43], 0, v[30:31]
	v_lshl_add_u64 v[54:55], v[44:45], 0, v[54:55]
	v_lshl_add_u64 v[56:57], v[46:47], 0, v[56:57]
	v_mov_b32_e32 v61, v113
	global_load_ushort v85, v[52:53], off
	global_load_ushort v86, v[54:55], off
	s_add_i32 s15, s16, 6
	global_load_dword v30, v[30:31], off
	s_add_i32 s18, s17, 5
	global_load_dword v31, v[56:57], off
	v_lshlrev_b64 v[56:57], 14, v[60:61]
	v_lshl_add_u64 v[58:59], v[48:49], 0, v[56:57]
	v_lshlrev_b64 v[56:57], 8, v[60:61]
	v_lshl_add_u64 v[56:57], v[50:51], 0, v[56:57]
	global_load_ushort v88, v[58:59], off
	global_load_dword v89, v[56:57], off
	v_mov_b32_e32 v56, s15
	v_mov_b32_e32 v57, s18
	v_cndmask_b32_e64 v112, v56, v57, s[6:7]
	v_cndmask_b32_e64 v64, v56, v57, s[4:5]
	v_cndmask_b32_e64 v66, v56, v57, s[8:9]
	v_lshlrev_b64 v[56:57], 15, v[112:113]
	v_mov_b32_e32 v65, v113
	v_lshl_add_u64 v[60:61], v[40:41], 0, v[56:57]
	v_lshlrev_b64 v[56:57], 9, v[112:113]
	v_lshlrev_b64 v[62:63], 15, v[64:65]
	v_lshlrev_b64 v[64:65], 9, v[64:65]
	v_lshl_add_u64 v[56:57], v[42:43], 0, v[56:57]
	v_lshl_add_u64 v[62:63], v[44:45], 0, v[62:63]
	v_lshl_add_u64 v[64:65], v[46:47], 0, v[64:65]
	v_mov_b32_e32 v67, v113
	global_load_ushort v87, v[60:61], off
	global_load_ushort v90, v[62:63], off
	s_add_i32 s18, s16, 5
	global_load_dword v56, v[56:57], off
	s_add_i32 s19, s17, 6
	global_load_dword v57, v[64:65], off
	v_lshlrev_b64 v[64:65], 14, v[66:67]
	v_lshlrev_b64 v[66:67], 8, v[66:67]
	v_lshl_add_u64 v[64:65], v[48:49], 0, v[64:65]
	v_lshl_add_u64 v[66:67], v[50:51], 0, v[66:67]
	global_load_ushort v92, v[64:65], off
	global_load_dword v93, v[66:67], off
	v_mov_b32_e32 v66, s18
	v_mov_b32_e32 v67, s19
	v_cndmask_b32_e64 v112, v66, v67, s[6:7]
	v_cndmask_b32_e64 v72, v66, v67, s[4:5]
	v_cndmask_b32_e64 v74, v66, v67, s[8:9]
	v_lshlrev_b64 v[66:67], 15, v[112:113]
	v_mov_b32_e32 v73, v113
	v_lshl_add_u64 v[68:69], v[40:41], 0, v[66:67]
	v_lshlrev_b64 v[66:67], 9, v[112:113]
	v_lshlrev_b64 v[70:71], 15, v[72:73]
	v_lshlrev_b64 v[72:73], 9, v[72:73]
	v_lshl_add_u64 v[66:67], v[42:43], 0, v[66:67]
	v_lshl_add_u64 v[70:71], v[44:45], 0, v[70:71]
	v_lshl_add_u64 v[72:73], v[46:47], 0, v[72:73]
	v_mov_b32_e32 v75, v113
	global_load_ushort v91, v[68:69], off
	global_load_ushort v94, v[70:71], off
	s_add_i32 s19, s16, 4
	global_load_dword v66, v[66:67], off
	s_add_i32 s20, s17, 7
	global_load_dword v67, v[72:73], off
	v_lshlrev_b64 v[72:73], 14, v[74:75]
	v_lshlrev_b64 v[74:75], 8, v[74:75]
	v_lshl_add_u64 v[72:73], v[48:49], 0, v[72:73]
	v_lshl_add_u64 v[74:75], v[50:51], 0, v[74:75]
	global_load_ushort v97, v[72:73], off
	global_load_dword v98, v[74:75], off
	v_mov_b32_e32 v74, s19
	v_mov_b32_e32 v75, s20
	v_cndmask_b32_e64 v112, v74, v75, s[6:7]
	v_cndmask_b32_e64 v80, v74, v75, s[4:5]
	v_cndmask_b32_e64 v102, v74, v75, s[8:9]
	v_lshlrev_b64 v[74:75], 15, v[112:113]
	v_mov_b32_e32 v81, v113
	v_lshl_add_u64 v[76:77], v[40:41], 0, v[74:75]
	v_lshlrev_b64 v[74:75], 9, v[112:113]
	v_lshlrev_b64 v[78:79], 15, v[80:81]
	v_lshlrev_b64 v[80:81], 9, v[80:81]
	v_lshl_add_u64 v[74:75], v[42:43], 0, v[74:75]
	v_lshl_add_u64 v[78:79], v[44:45], 0, v[78:79]
	v_lshl_add_u64 v[80:81], v[46:47], 0, v[80:81]
	v_mov_b32_e32 v103, v113
	global_load_ushort v95, v[76:77], off
	global_load_ushort v96, v[78:79], off
	s_add_i32 s19, s16, 11
	global_load_dword v74, v[74:75], off
	s_add_i32 s14, s17, 1
	global_load_dword v75, v[80:81], off
	v_lshlrev_b64 v[80:81], 14, v[102:103]
	v_lshlrev_b64 v[102:103], 8, v[102:103]
	v_lshl_add_u64 v[80:81], v[48:49], 0, v[80:81]
	v_lshl_add_u64 v[102:103], v[50:51], 0, v[102:103]
	global_load_ushort v99, v[80:81], off
	global_load_dword v100, v[102:103], off
	v_mov_b32_e32 v102, s19
	v_mov_b32_e32 v103, s17
	v_cndmask_b32_e64 v104, v102, v103, s[6:7]
	v_cndmask_b32_e64 v105, v102, v103, s[4:5]
	v_cndmask_b32_e64 v106, v102, v103, s[8:9]
	v_bfe_u32 v102, v82, 16, 1
	v_lshlrev_b32_e32 v112, 15, v104
	v_add3_u32 v107, v82, v102, s1
	v_lshl_add_u64 v[102:103], v[40:41], 0, v[112:113]
	global_store_short_d16_hi v[102:103], v107, off
	v_bfe_u32 v102, v83, 16, 1
	v_lshlrev_b32_e32 v112, 15, v105
	v_add3_u32 v104, v83, v102, s1
	v_lshl_add_u64 v[102:103], v[44:45], 0, v[112:113]
	global_store_short_d16_hi v[102:103], v104, off
	v_bfe_u32 v102, v101, 16, 1
	v_lshlrev_b32_e32 v112, 14, v106
	v_lshlrev_b32_e32 v108, 16, v28
	s_add_i32 s19, s16, 10
	v_add3_u32 v104, v101, v102, s1
	v_lshl_add_u64 v[102:103], v[48:49], 0, v[112:113]
	v_fmac_f32_e32 v108, v101, v8
	v_mov_b32_e32 v8, s19
	v_mov_b32_e32 v101, s14
	v_mov_b32_e32 v110, v0
	v_mov_b32_e32 v111, v4
	v_lshlrev_b32_e32 v115, 16, v26
	v_lshlrev_b32_e32 v114, 16, v24
	global_store_short_d16_hi v[102:103], v104, off
	v_cndmask_b32_e64 v102, v8, v101, s[6:7]
	v_pk_fma_f32 v[82:83], v[82:83], v[110:111], v[114:115]
	v_lshlrev_b32_e32 v112, 15, v102
	v_bfe_u32 v0, v82, 16, 1
	v_cndmask_b32_e64 v104, v8, v101, s[4:5]
	v_lshl_add_u64 v[102:103], v[40:41], 0, v[112:113]
	v_add3_u32 v0, v82, v0, s1
	v_lshlrev_b32_e32 v112, 15, v104
	global_store_short_d16_hi v[102:103], v0, off
	v_bfe_u32 v0, v83, 16, 1
	s_add_i32 s15, s17, 2
	v_cndmask_b32_e64 v8, v8, v101, s[8:9]
	v_lshl_add_u64 v[104:105], v[44:45], 0, v[112:113]
	v_and_b32_e32 v28, 0xffff0000, v28
	s_add_i32 s14, s16, 9
	v_add3_u32 v0, v83, v0, s1
	v_bfe_u32 v101, v108, 16, 1
	v_lshlrev_b32_e32 v112, 14, v8
	v_fmac_f32_e32 v28, v9, v108
	v_mov_b32_e32 v8, s14
	v_mov_b32_e32 v9, s15
	global_store_short_d16_hi v[104:105], v0, off
	v_mov_b32_e32 v4, v1
	v_and_b32_e32 v1, 0xffff0000, v26
	v_and_b32_e32 v0, 0xffff0000, v24
	v_add3_u32 v101, v108, v101, s1
	v_cndmask_b32_e64 v108, v8, v9, s[6:7]
	v_pk_fma_f32 v[0:1], v[4:5], v[82:83], v[0:1]
	v_lshl_add_u64 v[106:107], v[48:49], 0, v[112:113]
	v_lshlrev_b32_e32 v112, 15, v108
	v_bfe_u32 v4, v0, 16, 1
	v_cndmask_b32_e64 v109, v8, v9, s[4:5]
	v_cndmask_b32_e64 v116, v8, v9, s[8:9]
	v_lshl_add_u64 v[8:9], v[40:41], 0, v[112:113]
	v_add3_u32 v4, v0, v4, s1
	v_lshlrev_b32_e32 v112, 15, v109
	global_store_short_d16_hi v[106:107], v101, off
	global_store_short_d16_hi v[8:9], v4, off
	v_bfe_u32 v4, v1, 16, 1
	v_lshl_add_u64 v[108:109], v[44:45], 0, v[112:113]
	v_add3_u32 v4, v1, v4, s1
	global_store_short_d16_hi v[108:109], v4, off
	v_mov_b32_e32 v4, v2
	v_bfe_u32 v2, v28, 16, 1
	v_lshlrev_b32_e32 v112, 14, v116
	v_add3_u32 v2, v28, v2, s1
	v_lshl_add_u64 v[82:83], v[48:49], 0, v[112:113]
	s_add_i32 s18, s17, 3
	global_store_short_d16_hi v[82:83], v2, off
	v_lshlrev_b32_e32 v2, 16, v29
	s_add_i32 s14, s16, 8
	v_mov_b32_e32 v5, v6
	v_lshlrev_b32_e32 v9, 16, v27
	v_lshlrev_b32_e32 v8, 16, v25
	v_fmac_f32_e32 v2, v10, v28
	v_mov_b32_e32 v6, s14
	v_mov_b32_e32 v10, s18
	v_cndmask_b32_e64 v24, v6, v10, s[6:7]
	v_pk_fma_f32 v[0:1], v[4:5], v[0:1], v[8:9]
	v_lshlrev_b32_e32 v112, 15, v24
	v_bfe_u32 v4, v0, 16, 1
	v_cndmask_b32_e64 v26, v6, v10, s[4:5]
	v_lshl_add_u64 v[82:83], v[40:41], 0, v[112:113]
	v_add3_u32 v4, v0, v4, s1
	v_lshlrev_b32_e32 v112, 15, v26
	global_store_short_d16_hi v[82:83], v4, off
	v_bfe_u32 v4, v1, 16, 1
	s_add_i32 s18, s17, 8
	v_cndmask_b32_e64 v6, v6, v10, s[8:9]
	v_lshl_add_u64 v[102:103], v[44:45], 0, v[112:113]
	v_add3_u32 v4, v1, v4, s1
	s_cmpk_gt_u32 s17, 0xf7
	global_store_short_d16_hi v[102:103], v4, off
	v_bfe_u32 v4, v2, 16, 1
	v_lshlrev_b32_e32 v112, 14, v6
	s_cselect_b64 s[14:15], -1, 0
	v_add3_u32 v8, v2, v4, s1
	v_lshl_add_u64 v[4:5], v[48:49], 0, v[112:113]
	s_and_b64 vcc, exec, s[14:15]
	global_store_short_d16_hi v[4:5], v8, off
	s_cbranch_vccnz .Lat_p2_last
; __device__ __forceinline__ void pass2_triple(const KArgs& a, int t) {
;     ...
;     for (int sb = 0; sb < NCH; sb += 8) {
;         P2_LOAD(uB, dB, sb + 4);
;         P2_STEP(uA, dA, sb);
;         if (sb + 8 < NCH) P2_LOAD(uA, dA, sb + 8);
;         P2_STEP(uB, dB, sb + 4);
;     }
	s_add_i32 s19, s16, 3
	v_mov_b32_e32 v5, s19
	v_mov_b32_e32 v6, s18
	v_cndmask_b32_e64 v112, v5, v6, s[6:7]
	v_cndmask_b32_e64 v4, v5, v6, s[4:5]
	v_cndmask_b32_e64 v8, v5, v6, s[8:9]
	v_mov_b32_e32 v5, v113
	v_lshlrev_b64 v[12:13], 15, v[112:113]
	v_lshlrev_b64 v[14:15], 15, v[4:5]
	v_lshlrev_b64 v[4:5], 9, v[4:5]
	v_lshl_add_u64 v[12:13], v[40:41], 0, v[12:13]
	v_lshl_add_u64 v[4:5], v[46:47], 0, v[4:5]
	v_mov_b32_e32 v9, v113
	global_load_ushort v120, v[12:13], off
	global_load_dword v16, v[4:5], off
	v_lshlrev_b64 v[12:13], 9, v[112:113]
	v_lshlrev_b64 v[4:5], 14, v[8:9]
	v_lshl_add_u64 v[12:13], v[42:43], 0, v[12:13]
	v_lshl_add_u64 v[4:5], v[48:49], 0, v[4:5]
	global_load_dword v12, v[12:13], off
	v_lshl_add_u64 v[14:15], v[44:45], 0, v[14:15]
	global_load_ushort v122, v[4:5], off
	v_lshlrev_b64 v[4:5], 8, v[8:9]
	v_lshl_add_u64 v[4:5], v[50:51], 0, v[4:5]
	s_add_i32 s19, s17, 9
	s_add_i32 s20, s16, 2
	global_load_ushort v121, v[14:15], off
	global_load_dword v20, v[4:5], off
	v_mov_b32_e32 v5, s20
	v_mov_b32_e32 v8, s19
	v_cndmask_b32_e64 v112, v5, v8, s[6:7]
	v_lshlrev_b64 v[14:15], 15, v[112:113]
	v_lshl_add_u64 v[14:15], v[40:41], 0, v[14:15]
	global_load_ushort v123, v[14:15], off
	v_lshlrev_b64 v[14:15], 9, v[112:113]
	v_cndmask_b32_e64 v4, v5, v8, s[4:5]
	v_cndmask_b32_e64 v8, v5, v8, s[8:9]
	v_lshl_add_u64 v[14:15], v[42:43], 0, v[14:15]
	v_mov_b32_e32 v5, v113
	global_load_dword v13, v[14:15], off
	v_lshlrev_b64 v[14:15], 15, v[4:5]
	v_lshlrev_b64 v[4:5], 9, v[4:5]
	v_lshl_add_u64 v[14:15], v[44:45], 0, v[14:15]
	v_lshl_add_u64 v[4:5], v[46:47], 0, v[4:5]
	global_load_ushort v124, v[14:15], off
	global_load_dword v17, v[4:5], off
	v_lshlrev_b64 v[4:5], 14, v[8:9]
	v_lshl_add_u64 v[4:5], v[48:49], 0, v[4:5]
	global_load_ushort v34, v[4:5], off
	v_lshlrev_b64 v[4:5], 8, v[8:9]
	v_lshl_add_u64 v[4:5], v[50:51], 0, v[4:5]
	s_add_i32 s19, s17, 10
	s_add_i32 s20, s16, 1
	global_load_dword v21, v[4:5], off
	v_mov_b32_e32 v5, s20
	v_mov_b32_e32 v8, s19
	v_cndmask_b32_e64 v112, v5, v8, s[6:7]
	v_cndmask_b32_e64 v4, v5, v8, s[4:5]
	v_cndmask_b32_e64 v8, v5, v8, s[8:9]
	v_mov_b32_e32 v5, v113
	v_lshlrev_b64 v[14:15], 15, v[112:113]
	v_lshlrev_b64 v[18:19], 15, v[4:5]
	v_lshlrev_b64 v[4:5], 9, v[4:5]
	v_lshl_add_u64 v[14:15], v[40:41], 0, v[14:15]
	v_lshl_add_u64 v[18:19], v[44:45], 0, v[18:19]
	v_lshl_add_u64 v[4:5], v[46:47], 0, v[4:5]
	global_load_ushort v38, v[14:15], off
	global_load_ushort v35, v[18:19], off
	s_add_i32 s17, s17, 11
	global_load_dword v18, v[4:5], off
	v_lshlrev_b64 v[14:15], 9, v[112:113]
	v_lshlrev_b64 v[4:5], 14, v[8:9]
	v_lshl_add_u64 v[14:15], v[42:43], 0, v[14:15]
	v_lshl_add_u64 v[4:5], v[48:49], 0, v[4:5]
	global_load_dword v14, v[14:15], off
	s_mov_b32 s0, 0x5040100
	global_load_ushort v36, v[4:5], off
	v_lshlrev_b64 v[4:5], 8, v[8:9]
	v_lshl_add_u64 v[4:5], v[50:51], 0, v[4:5]
	global_load_dword v22, v[4:5], off
	v_mov_b32_e32 v5, s16
	v_mov_b32_e32 v8, s17
	v_cndmask_b32_e64 v112, v5, v8, s[6:7]
	v_lshlrev_b64 v[32:33], 15, v[112:113]
	v_lshl_add_u64 v[32:33], v[40:41], 0, v[32:33]
	global_load_ushort v39, v[32:33], off
	v_lshlrev_b64 v[32:33], 9, v[112:113]
	v_cndmask_b32_e64 v4, v5, v8, s[4:5]
	v_cndmask_b32_e64 v8, v5, v8, s[8:9]
	v_lshl_add_u64 v[32:33], v[42:43], 0, v[32:33]
	v_mov_b32_e32 v5, v113
	global_load_dword v15, v[32:33], off
	v_lshlrev_b64 v[32:33], 15, v[4:5]
	v_lshlrev_b64 v[4:5], 9, v[4:5]
	v_lshl_add_u64 v[32:33], v[44:45], 0, v[32:33]
	v_lshl_add_u64 v[4:5], v[46:47], 0, v[4:5]
	global_load_ushort v125, v[32:33], off
	global_load_dword v19, v[4:5], off
	v_lshlrev_b64 v[32:33], 14, v[8:9]
	v_lshl_add_u64 v[32:33], v[48:49], 0, v[32:33]
	v_lshlrev_b64 v[4:5], 8, v[8:9]
	global_load_ushort v32, v[32:33], off
	v_lshl_add_u64 v[4:5], v[50:51], 0, v[4:5]
	global_load_dword v23, v[4:5], off
	s_waitcnt vmcnt(24) lgkmcnt(0)
	s_branch .LBB0_342
.Lat_p2_last:
	s_waitcnt vmcnt(0) lgkmcnt(0)
	s_branch .LBB0_342

;     __host__ __device__ bool next(int i, Unit& u) const {
;         const long L = (long)i * G + c; if (L >= nwg) return false;
;         int wgid = (int)L; { const int q = nwg / NXCD, r = nwg % NXCD, xcd = wgid % NXCD, off = wgid / NXCD; wgid = (xcd < r ? xcd * (q + 1) : r * (q + 1) + (xcd - r) * q) + off; }
;         const int nig = WGM * nN, gid = wgid / nig, fm = gid * WGM, gsz = (nM - fm) < WGM ? (nM - fm) : WGM;
;         u.pm = fm + ((wgid % nig) % gsz); u.pn = (wgid % nig) / gsz; return true;
;     }
; template <class Epi, class Sched, bool ALIGN_EPI = false, bool SP2 = false>
; __device__ __forceinline__ void gemm_phase(PG8_LAS unsigned char* lds, const Gemm g, const Sched& S, const Epi& E) {
;     ...
;         const bool has_next = S.next(ui + 1, nxt);
.LBB0_719:
	v_lshl_add_u32 v230, s43, 8, v138
	v_ashrrev_i32_e32 v231, 31, v230
	v_lshl_add_u64 v[230:231], v[230:231], 2, s[12:13]
	global_load_dword v222, v[230:231], off
	global_load_dword v223, v[230:231], off offset:64
	global_load_dword v224, v[230:231], off offset:128
	global_load_dword v225, v[230:231], off offset:192
	global_load_dword v226, v[230:231], off offset:512
	global_load_dword v227, v[230:231], off offset:576
	global_load_dword v228, v[230:231], off offset:640
	global_load_dword v229, v[230:231], off offset:704
	s_add_i32 s41, s41, 1
	s_mul_i32 s6, s41, s71
	s_mul_hi_u32 s7, s41, s70
	s_add_i32 s7, s7, s6
	s_mul_i32 s6, s41, s70
	v_readlane_b32 s20, v255, 1
	v_readlane_b32 s21, v255, 2
	s_add_u32 s20, s6, s20
	s_addc_u32 s21, s7, s21
	v_mov_b64_e32 v[0:1], 0x1600
	v_cmp_lt_i64_e64 s[6:7], s[20:21], v[0:1]
	v_mov_b64_e32 v[0:1], 0x15ff
	v_cmp_gt_i64_e32 vcc, s[20:21], v[0:1]
	s_cbranch_vccnz .LBB0_721
	s_ashr_i32 s16, s20, 31
	s_lshr_b32 s16, s16, 29
	s_add_i32 s16, s20, s16
	s_ashr_i32 s17, s16, 3
	s_and_b32 s16, s16, -8
	s_sub_i32 s16, s20, s16
	s_cmp_lt_i32 s16, 0
	s_movk_i32 s18, 0x2c1
	s_cselect_b32 s18, s18, 0x2c0
	s_mul_i32 s16, s16, s18
	s_add_i32 s16, s16, s17
	s_mul_hi_i32 s17, s16, 0x2e8ba2e9
	s_lshr_b32 s18, s17, 31
	s_ashr_i32 s17, s17, 6
	s_add_i32 s17, s17, s18
	s_lshl_b32 s18, s17, 3
	s_sub_i32 s19, 0x80, s18
	s_min_i32 s19, s19, 8
	s_abs_i32 s20, s19
	v_cvt_f32_u32_e32 v0, s20
	s_sub_i32 s22, 0, s20
	s_mulk_i32 s17, 0x160
	s_sub_i32 s17, s16, s17
	v_rcp_iflag_f32_e32 v0, v0
	s_abs_i32 s16, s17
	s_xor_b32 s21, s17, s19
	s_ashr_i32 s21, s21, 31
	v_mul_f32_e32 v0, 0x4f7ffffe, v0
	v_cvt_u32_f32_e32 v0, v0
	s_nop 0
	v_readfirstlane_b32 s23, v0
	s_mul_i32 s22, s22, s23
	s_mul_hi_u32 s22, s23, s22
	s_add_i32 s23, s23, s22
	s_mul_hi_u32 s22, s16, s23
	s_mul_i32 s23, s22, s20
	s_sub_i32 s16, s16, s23
	s_add_i32 s28, s22, 1
	s_sub_i32 s23, s16, s20
	s_cmp_ge_u32 s16, s20
	s_cselect_b32 s22, s28, s22
	s_cselect_b32 s16, s23, s16
	s_add_i32 s23, s22, 1
	s_cmp_ge_u32 s16, s20
	s_cselect_b32 s16, s23, s22
	s_xor_b32 s16, s16, s21
	s_sub_i32 s16, s16, s21
	s_mul_i32 s19, s16, s19
	s_sub_i32 s17, s17, s19
	s_add_i32 s18, s18, s17

;     __device__ __forceinline__ void operator()(const f32x4 (&acc)[2][2][4][2], const Unit& u, int wr, int wc, int fr, int fq) const {
;     ...
;             for (int m = 0; m < 4; ++m) rsv[ai][m] = row_stat(rsq, slots, row0 + ai * HALF + m * 16, fq);
; #pragma unroll
;         for (int ai = 0; ai < 2; ++ai)
; #pragma unroll
;             for (int m = 0; m < 4; ++m) { bf16_t* rowp = H + (size_t)(row0 + ai * HALF + m * 16) * DFF;
;                 const float rs = rsqrtf(rsv[ai][m] * (1.f / DM) + EPS);
; #pragma unroll
;                 for (int bj = 0; bj < 2; ++bj) { const f32x4 a = acc[ai][bj][m][0] * rs, g = acc[ai][bj][m][1] * rs;
.LBB0_725:
	v_lshl_add_u32 v154, s43, 8, v138
	v_ashrrev_i32_e32 v155, 31, v154
	v_mov_b32_e32 v156, v222
	v_mov_b32_e32 v162, v223
	v_mov_b32_e32 v152, v224
	v_mov_b32_e32 v150, v225
	v_mov_b32_e32 v148, v226
	v_mov_b32_e32 v146, v227
	v_mov_b32_e32 v144, v228
	v_mov_b32_e32 v142, v229
	v_or_b32_e32 v157, 16, v154
	v_mov_b64_e32 v[136:137], s[10:11]
	s_movk_i32 s0, 0x2c00
	v_or_b32_e32 v153, 32, v154
	v_or_b32_e32 v151, 48, v154
	v_add_u32_e32 v149, 0x80, v154
	v_add_u32_e32 v147, 0x90, v154
	v_add_u32_e32 v145, 0xa0, v154
	v_add_u32_e32 v143, 0xb0, v154
	v_mad_i64_i32 v[154:155], s[24:25], v154, s0, v[136:137]
	s_waitcnt lgkmcnt(0)
	v_fmamk_f32 v156, v156, 0x3a000000, v194
	v_cmp_gt_f32_e32 vcc, s33, v156
	v_mul_f32_e32 v158, 0x4b800000, v156
	s_nop 0
	v_cndmask_b32_e32 v156, v156, v158, vcc
	v_rsq_f32_e32 v156, v156
	s_nop 0
	v_mul_f32_e32 v158, 0x45800000, v156
	v_cndmask_b32_e32 v156, v156, v158, vcc
	v_pk_mul_f32 v[126:127], v[126:127], v[156:157] op_sel_hi:[1,0]
	v_pk_mul_f32 v[122:123], v[122:123], v[156:157] op_sel_hi:[1,0]
	v_mul_f32_e32 v159, 0xbfb8aa3b, v126
	v_exp_f32_e32 v159, v159
	v_pk_mul_f32 v[128:129], v[128:129], v[156:157] op_sel_hi:[1,0]
	v_pk_mul_f32 v[124:125], v[124:125], v[156:157] op_sel_hi:[1,0]
	v_lshl_or_b32 v158, s42, 7, v140
	v_add_f32_e32 v159, 1.0, v159
	v_rcp_f32_e32 v160, v159
	v_mul_f32_e32 v159, 0xbfb8aa3b, v127
	v_exp_f32_e32 v159, v159
	v_pk_mul_f32 v[118:119], v[118:119], v[156:157] op_sel_hi:[1,0]
	v_pk_mul_f32 v[114:115], v[114:115], v[156:157] op_sel_hi:[1,0]
	v_pk_mul_f32 v[120:121], v[120:121], v[156:157] op_sel_hi:[1,0]
	v_add_f32_e32 v159, 1.0, v159
	v_rcp_f32_e32 v161, v159
	v_ashrrev_i32_e32 v159, 31, v158
	v_pk_mul_f32 v[116:117], v[116:117], v[156:157] op_sel_hi:[1,0]
	v_pk_mul_f32 v[126:127], v[126:127], v[160:161]
	s_nop 0
	v_pk_mul_f32 v[122:123], v[122:123], v[126:127]
	s_nop 0
	v_cvt_pk_bf16_f32 v126, v122, v123
	v_mul_f32_e32 v122, 0xbfb8aa3b, v128
	v_mul_f32_e32 v123, 0xbfb8aa3b, v129
	v_exp_f32_e32 v122, v122
	v_exp_f32_e32 v123, v123
	v_add_f32_e32 v122, 1.0, v122
	v_add_f32_e32 v123, 1.0, v123
	v_rcp_f32_e32 v122, v122
	v_rcp_f32_e32 v123, v123
	s_nop 0
	v_pk_mul_f32 v[122:123], v[128:129], v[122:123]
	s_nop 0
	v_pk_mul_f32 v[122:123], v[124:125], v[122:123]
	s_nop 0
	v_cvt_pk_bf16_f32 v127, v122, v123
	v_lshlrev_b64 v[122:123], 1, v[158:159]
	v_lshl_add_u64 v[124:125], v[154:155], 0, v[122:123]
	global_store_dwordx2 v[124:125], v[126:127], off
	v_mul_f32_e32 v126, 0xbfb8aa3b, v118
	v_mul_f32_e32 v127, 0xbfb8aa3b, v119
	v_exp_f32_e32 v126, v126
	v_exp_f32_e32 v127, v127
	v_add_f32_e32 v126, 1.0, v126
	v_add_f32_e32 v127, 1.0, v127
	v_rcp_f32_e32 v126, v126
	v_rcp_f32_e32 v127, v127
	s_nop 0
	v_pk_mul_f32 v[118:119], v[118:119], v[126:127]
	s_nop 0
	v_pk_mul_f32 v[114:115], v[114:115], v[118:119]
	s_nop 0
	v_cvt_pk_bf16_f32 v114, v114, v115
	v_mul_f32_e32 v115, 0xbfb8aa3b, v120
	v_exp_f32_e32 v115, v115
	s_nop 0
	v_add_f32_e32 v115, 1.0, v115
	v_rcp_f32_e32 v118, v115
	v_mul_f32_e32 v115, 0xbfb8aa3b, v121
	v_exp_f32_e32 v115, v115
	s_nop 0
	v_add_f32_e32 v115, 1.0, v115
	v_rcp_f32_e32 v119, v115
	s_nop 0
	v_pk_mul_f32 v[118:119], v[120:121], v[118:119]
	s_nop 0
	v_pk_mul_f32 v[116:117], v[116:117], v[118:119]
	s_nop 0
	v_cvt_pk_bf16_f32 v115, v116, v117
	v_fmamk_f32 v116, v162, 0x3a000000, v194
	v_cmp_gt_f32_e32 vcc, s33, v116
	v_mul_f32_e32 v117, 0x4b800000, v116
	global_store_dwordx2 v[124:125], v[114:115], off offset:128
	v_cndmask_b32_e32 v116, v116, v117, vcc
	v_rsq_f32_e32 v116, v116
	v_mad_i64_i32 v[114:115], s[24:25], v157, s0, v[136:137]
	v_mul_f32_e32 v117, 0x45800000, v116
	v_cndmask_b32_e32 v116, v116, v117, vcc
	v_pk_mul_f32 v[108:109], v[108:109], v[116:117] op_sel_hi:[1,0]
	v_pk_mul_f32 v[110:111], v[110:111], v[116:117] op_sel_hi:[1,0]
	v_pk_mul_f32 v[106:107], v[106:107], v[116:117] op_sel_hi:[1,0]
	v_pk_mul_f32 v[104:105], v[104:105], v[116:117] op_sel_hi:[1,0]
	v_mul_f32_e32 v117, 0xbfb8aa3b, v108
	v_exp_f32_e32 v117, v117
	s_nop 0
	v_add_f32_e32 v117, 1.0, v117
	v_rcp_f32_e32 v118, v117
	v_mul_f32_e32 v117, 0xbfb8aa3b, v109
	v_exp_f32_e32 v117, v117
	s_nop 0
	v_add_f32_e32 v117, 1.0, v117
	v_rcp_f32_e32 v119, v117
	v_pk_mul_f32 v[100:101], v[100:101], v[116:117] op_sel_hi:[1,0]
	v_pk_mul_f32 v[96:97], v[96:97], v[116:117] op_sel_hi:[1,0]
	v_pk_mul_f32 v[102:103], v[102:103], v[116:117] op_sel_hi:[1,0]
	v_pk_mul_f32 v[108:109], v[108:109], v[118:119]
	v_pk_mul_f32 v[98:99], v[98:99], v[116:117] op_sel_hi:[1,0]
	v_pk_mul_f32 v[104:105], v[104:105], v[108:109]
	s_nop 0
	v_cvt_pk_bf16_f32 v104, v104, v105
	v_mul_f32_e32 v105, 0xbfb8aa3b, v110
	v_exp_f32_e32 v105, v105
	s_nop 0
	v_add_f32_e32 v105, 1.0, v105
	v_rcp_f32_e32 v108, v105
	v_mul_f32_e32 v105, 0xbfb8aa3b, v111
	v_exp_f32_e32 v105, v105
	s_nop 0
	v_add_f32_e32 v105, 1.0, v105
	v_rcp_f32_e32 v109, v105
	s_nop 0
	v_pk_mul_f32 v[108:109], v[110:111], v[108:109]
	s_nop 0
	v_pk_mul_f32 v[106:107], v[106:107], v[108:109]
	s_nop 0
	v_cvt_pk_bf16_f32 v105, v106, v107
	v_lshl_add_u64 v[106:107], v[114:115], 0, v[122:123]
	global_store_dwordx2 v[106:107], v[104:105], off
	v_mul_f32_e32 v104, 0xbfb8aa3b, v100
	v_mul_f32_e32 v105, 0xbfb8aa3b, v101
	v_exp_f32_e32 v104, v104
	v_exp_f32_e32 v105, v105
	v_add_f32_e32 v104, 1.0, v104
	v_add_f32_e32 v105, 1.0, v105
	v_rcp_f32_e32 v104, v104
	v_rcp_f32_e32 v105, v105
	s_nop 0
	v_pk_mul_f32 v[100:101], v[100:101], v[104:105]
	s_nop 0
	v_pk_mul_f32 v[96:97], v[96:97], v[100:101]
	s_nop 0
	v_cvt_pk_bf16_f32 v96, v96, v97
	v_mul_f32_e32 v97, 0xbfb8aa3b, v102
	v_exp_f32_e32 v97, v97
	s_nop 0
	v_add_f32_e32 v97, 1.0, v97
	v_rcp_f32_e32 v100, v97
	v_mul_f32_e32 v97, 0xbfb8aa3b, v103
; __device__ __forceinline__ unsigned cvt_pk_bf16(float lo, float hi) { f32x2 v = {lo, hi}; bf16x2_t b = __builtin_convertvector(v, bf16x2_t); return __builtin_bit_cast(unsigned, b); }
; __device__ __forceinline__ float silu_(float z) { return z * sigmoid_(z); }
;     __device__ __forceinline__ void operator()(const f32x4 (&acc)[2][2][4][2], const Unit& u, int wr, int wc, int fr, int fq) const {
;     ...
;             for (int m = 0; m < 4; ++m) { bf16_t* rowp = H + (size_t)(row0 + ai * HALF + m * 16) * DFF;
;                 const float rs = rsqrtf(rsv[ai][m] * (1.f / DM) + EPS);
; #pragma unroll
;                 for (int bj = 0; bj < 2; ++bj) { const f32x4 a = acc[ai][bj][m][0] * rs, g = acc[ai][bj][m][1] * rs;
;                     const int col = 16 * (8 * u.pn + 4 * bj + wc) + 4 * fq;
;                     u32x2 w; w.x = cvt_pk_bf16(silu_(a[0]) * g[0], silu_(a[1]) * g[1]); w.y = cvt_pk_bf16(silu_(a[2]) * g[2], silu_(a[3]) * g[3]);
;                     *(u32x2*)(rowp + col) = w; } }
	v_exp_f32_e32 v97, v97
	s_nop 0
	v_add_f32_e32 v97, 1.0, v97
	v_rcp_f32_e32 v101, v97
	s_nop 0
	v_pk_mul_f32 v[100:101], v[102:103], v[100:101]
	s_nop 0
	v_pk_mul_f32 v[98:99], v[98:99], v[100:101]
	s_nop 0
	v_cvt_pk_bf16_f32 v97, v98, v99
	v_fmamk_f32 v98, v152, 0x3a000000, v194
	v_cmp_gt_f32_e32 vcc, s33, v98
	v_mul_f32_e32 v99, 0x4b800000, v98
	global_store_dwordx2 v[106:107], v[96:97], off offset:128
	v_cndmask_b32_e32 v98, v98, v99, vcc
	v_rsq_f32_e32 v98, v98
	v_mad_i64_i32 v[96:97], s[24:25], v153, s0, v[136:137]
	v_mul_f32_e32 v99, 0x45800000, v98
	v_cndmask_b32_e32 v98, v98, v99, vcc
	v_pk_mul_f32 v[92:93], v[92:93], v[98:99] op_sel_hi:[1,0]
	v_pk_mul_f32 v[94:95], v[94:95], v[98:99] op_sel_hi:[1,0]
	v_pk_mul_f32 v[90:91], v[90:91], v[98:99] op_sel_hi:[1,0]
	v_pk_mul_f32 v[88:89], v[88:89], v[98:99] op_sel_hi:[1,0]
	v_mul_f32_e32 v99, 0xbfb8aa3b, v92
	v_exp_f32_e32 v99, v99
	s_nop 0
	v_add_f32_e32 v99, 1.0, v99
	v_rcp_f32_e32 v100, v99
	v_mul_f32_e32 v99, 0xbfb8aa3b, v93
	v_exp_f32_e32 v99, v99
	s_nop 0
	v_add_f32_e32 v99, 1.0, v99
	v_rcp_f32_e32 v101, v99
	v_pk_mul_f32 v[84:85], v[84:85], v[98:99] op_sel_hi:[1,0]
	v_pk_mul_f32 v[80:81], v[80:81], v[98:99] op_sel_hi:[1,0]
	v_pk_mul_f32 v[86:87], v[86:87], v[98:99] op_sel_hi:[1,0]
	v_pk_mul_f32 v[92:93], v[92:93], v[100:101]
	v_pk_mul_f32 v[82:83], v[82:83], v[98:99] op_sel_hi:[1,0]
	v_pk_mul_f32 v[88:89], v[88:89], v[92:93]
	s_nop 0
	v_cvt_pk_bf16_f32 v88, v88, v89
	v_mul_f32_e32 v89, 0xbfb8aa3b, v94
	v_exp_f32_e32 v89, v89
	s_nop 0
	v_add_f32_e32 v89, 1.0, v89
	v_rcp_f32_e32 v92, v89
	v_mul_f32_e32 v89, 0xbfb8aa3b, v95
	v_exp_f32_e32 v89, v89
	s_nop 0
	v_add_f32_e32 v89, 1.0, v89
	v_rcp_f32_e32 v93, v89
	s_nop 0
	v_pk_mul_f32 v[92:93], v[94:95], v[92:93]
	s_nop 0
	v_pk_mul_f32 v[90:91], v[90:91], v[92:93]
	s_nop 0
	v_cvt_pk_bf16_f32 v89, v90, v91
	v_lshl_add_u64 v[90:91], v[96:97], 0, v[122:123]
	global_store_dwordx2 v[90:91], v[88:89], off
	v_mul_f32_e32 v88, 0xbfb8aa3b, v84
	v_mul_f32_e32 v89, 0xbfb8aa3b, v85
	v_exp_f32_e32 v88, v88
	v_exp_f32_e32 v89, v89
	v_add_f32_e32 v88, 1.0, v88
	v_add_f32_e32 v89, 1.0, v89
	v_rcp_f32_e32 v88, v88
	v_rcp_f32_e32 v89, v89
	s_nop 0
	v_pk_mul_f32 v[84:85], v[84:85], v[88:89]
	s_nop 0
	v_pk_mul_f32 v[80:81], v[80:81], v[84:85]
	s_nop 0
	v_cvt_pk_bf16_f32 v80, v80, v81
	v_mul_f32_e32 v81, 0xbfb8aa3b, v86
	v_exp_f32_e32 v81, v81
	s_nop 0
	v_add_f32_e32 v81, 1.0, v81
	v_rcp_f32_e32 v84, v81
	v_mul_f32_e32 v81, 0xbfb8aa3b, v87
	v_exp_f32_e32 v81, v81
	s_nop 0
	v_add_f32_e32 v81, 1.0, v81
	v_rcp_f32_e32 v85, v81
	s_nop 0
	v_pk_mul_f32 v[84:85], v[86:87], v[84:85]
	s_nop 0
	v_pk_mul_f32 v[82:83], v[82:83], v[84:85]
	s_nop 0
	v_cvt_pk_bf16_f32 v81, v82, v83
	v_fmamk_f32 v82, v150, 0x3a000000, v194
	v_cmp_gt_f32_e32 vcc, s33, v82
	v_mul_f32_e32 v83, 0x4b800000, v82
	global_store_dwordx2 v[90:91], v[80:81], off offset:128
	v_cndmask_b32_e32 v82, v82, v83, vcc
	v_rsq_f32_e32 v82, v82
	v_mad_i64_i32 v[80:81], s[24:25], v151, s0, v[136:137]
	v_mul_f32_e32 v83, 0x45800000, v82
	v_cndmask_b32_e32 v82, v82, v83, vcc
	v_pk_mul_f32 v[76:77], v[76:77], v[82:83] op_sel_hi:[1,0]
	v_pk_mul_f32 v[78:79], v[78:79], v[82:83] op_sel_hi:[1,0]
	v_pk_mul_f32 v[74:75], v[74:75], v[82:83] op_sel_hi:[1,0]
	v_pk_mul_f32 v[72:73], v[72:73], v[82:83] op_sel_hi:[1,0]
	v_mul_f32_e32 v83, 0xbfb8aa3b, v76
	v_exp_f32_e32 v83, v83
	s_nop 0
	v_add_f32_e32 v83, 1.0, v83
	v_rcp_f32_e32 v84, v83
	v_mul_f32_e32 v83, 0xbfb8aa3b, v77
	v_exp_f32_e32 v83, v83
	s_nop 0
	v_add_f32_e32 v83, 1.0, v83
	v_rcp_f32_e32 v85, v83
	v_pk_mul_f32 v[68:69], v[68:69], v[82:83] op_sel_hi:[1,0]
	v_pk_mul_f32 v[64:65], v[64:65], v[82:83] op_sel_hi:[1,0]
	v_pk_mul_f32 v[70:71], v[70:71], v[82:83] op_sel_hi:[1,0]
	v_pk_mul_f32 v[76:77], v[76:77], v[84:85]
	v_pk_mul_f32 v[66:67], v[66:67], v[82:83] op_sel_hi:[1,0]
	v_pk_mul_f32 v[72:73], v[72:73], v[76:77]
	s_nop 0
	v_cvt_pk_bf16_f32 v72, v72, v73
	v_mul_f32_e32 v73, 0xbfb8aa3b, v78
	v_exp_f32_e32 v73, v73
	s_nop 0
	v_add_f32_e32 v73, 1.0, v73
	v_rcp_f32_e32 v76, v73
	v_mul_f32_e32 v73, 0xbfb8aa3b, v79
	v_exp_f32_e32 v73, v73
	s_nop 0
	v_add_f32_e32 v73, 1.0, v73
	v_rcp_f32_e32 v77, v73
	s_nop 0
	v_pk_mul_f32 v[76:77], v[78:79], v[76:77]
	s_nop 0
	v_pk_mul_f32 v[74:75], v[74:75], v[76:77]
	s_nop 0
	v_cvt_pk_bf16_f32 v73, v74, v75
	v_lshl_add_u64 v[74:75], v[80:81], 0, v[122:123]
	global_store_dwordx2 v[74:75], v[72:73], off
	v_mul_f32_e32 v72, 0xbfb8aa3b, v68
	v_mul_f32_e32 v73, 0xbfb8aa3b, v69
	v_exp_f32_e32 v72, v72
	v_exp_f32_e32 v73, v73
	v_add_f32_e32 v72, 1.0, v72
	v_add_f32_e32 v73, 1.0, v73
	v_rcp_f32_e32 v72, v72
	v_rcp_f32_e32 v73, v73
	s_nop 0
	v_pk_mul_f32 v[68:69], v[68:69], v[72:73]
	s_nop 0
	v_pk_mul_f32 v[64:65], v[64:65], v[68:69]
	s_nop 0
	v_cvt_pk_bf16_f32 v64, v64, v65
	v_mul_f32_e32 v65, 0xbfb8aa3b, v70
	v_exp_f32_e32 v65, v65
	s_nop 0
	v_add_f32_e32 v65, 1.0, v65
	v_rcp_f32_e32 v68, v65
	v_mul_f32_e32 v65, 0xbfb8aa3b, v71
	v_exp_f32_e32 v65, v65
	s_nop 0
	v_add_f32_e32 v65, 1.0, v65
	v_rcp_f32_e32 v69, v65
	s_nop 0
	v_pk_mul_f32 v[68:69], v[70:71], v[68:69]
	s_nop 0
	v_pk_mul_f32 v[66:67], v[66:67], v[68:69]
	s_nop 0
	v_cvt_pk_bf16_f32 v65, v66, v67
	v_fmamk_f32 v66, v148, 0x3a000000, v194
	v_cmp_gt_f32_e32 vcc, s33, v66
	v_mul_f32_e32 v67, 0x4b800000, v66
	global_store_dwordx2 v[74:75], v[64:65], off offset:128
	v_cndmask_b32_e32 v66, v66, v67, vcc
	v_rsq_f32_e32 v66, v66
	v_mad_i64_i32 v[64:65], s[24:25], v149, s0, v[136:137]
	v_mul_f32_e32 v67, 0x45800000, v66
	v_cndmask_b32_e32 v66, v66, v67, vcc
	v_pk_mul_f32 v[60:61], v[60:61], v[66:67] op_sel_hi:[1,0]
	v_pk_mul_f32 v[62:63], v[62:63], v[66:67] op_sel_hi:[1,0]
; __device__ __forceinline__ unsigned cvt_pk_bf16(float lo, float hi) { f32x2 v = {lo, hi}; bf16x2_t b = __builtin_convertvector(v, bf16x2_t); return __builtin_bit_cast(unsigned, b); }
; __device__ __forceinline__ float silu_(float z) { return z * sigmoid_(z); }
;     __device__ __forceinline__ void operator()(const f32x4 (&acc)[2][2][4][2], const Unit& u, int wr, int wc, int fr, int fq) const {
;     ...
;             for (int m = 0; m < 4; ++m) { bf16_t* rowp = H + (size_t)(row0 + ai * HALF + m * 16) * DFF;
;                 const float rs = rsqrtf(rsv[ai][m] * (1.f / DM) + EPS);
; #pragma unroll
;                 for (int bj = 0; bj < 2; ++bj) { const f32x4 a = acc[ai][bj][m][0] * rs, g = acc[ai][bj][m][1] * rs;
;                     const int col = 16 * (8 * u.pn + 4 * bj + wc) + 4 * fq;
;                     u32x2 w; w.x = cvt_pk_bf16(silu_(a[0]) * g[0], silu_(a[1]) * g[1]); w.y = cvt_pk_bf16(silu_(a[2]) * g[2], silu_(a[3]) * g[3]);
;                     *(u32x2*)(rowp + col) = w; } }
	v_pk_mul_f32 v[58:59], v[58:59], v[66:67] op_sel_hi:[1,0]
	v_pk_mul_f32 v[56:57], v[56:57], v[66:67] op_sel_hi:[1,0]
	v_mul_f32_e32 v67, 0xbfb8aa3b, v60
	v_exp_f32_e32 v67, v67
	s_nop 0
	v_add_f32_e32 v67, 1.0, v67
	v_rcp_f32_e32 v68, v67
	v_mul_f32_e32 v67, 0xbfb8aa3b, v61
	v_exp_f32_e32 v67, v67
	s_nop 0
	v_add_f32_e32 v67, 1.0, v67
	v_rcp_f32_e32 v69, v67
	v_pk_mul_f32 v[52:53], v[52:53], v[66:67] op_sel_hi:[1,0]
	v_pk_mul_f32 v[48:49], v[48:49], v[66:67] op_sel_hi:[1,0]
	v_pk_mul_f32 v[54:55], v[54:55], v[66:67] op_sel_hi:[1,0]
	v_pk_mul_f32 v[60:61], v[60:61], v[68:69]
	v_pk_mul_f32 v[50:51], v[50:51], v[66:67] op_sel_hi:[1,0]
	v_pk_mul_f32 v[56:57], v[56:57], v[60:61]
	s_nop 0
	v_cvt_pk_bf16_f32 v56, v56, v57
	v_mul_f32_e32 v57, 0xbfb8aa3b, v62
	v_exp_f32_e32 v57, v57
	s_nop 0
	v_add_f32_e32 v57, 1.0, v57
	v_rcp_f32_e32 v60, v57
	v_mul_f32_e32 v57, 0xbfb8aa3b, v63
	v_exp_f32_e32 v57, v57
	s_nop 0
	v_add_f32_e32 v57, 1.0, v57
	v_rcp_f32_e32 v61, v57
	s_nop 0
	v_pk_mul_f32 v[60:61], v[62:63], v[60:61]
	s_nop 0
	v_pk_mul_f32 v[58:59], v[58:59], v[60:61]
	s_nop 0
	v_cvt_pk_bf16_f32 v57, v58, v59
	v_lshl_add_u64 v[58:59], v[64:65], 0, v[122:123]
	global_store_dwordx2 v[58:59], v[56:57], off
	v_mul_f32_e32 v56, 0xbfb8aa3b, v52
	v_mul_f32_e32 v57, 0xbfb8aa3b, v53
	v_exp_f32_e32 v56, v56
	v_exp_f32_e32 v57, v57
	v_add_f32_e32 v56, 1.0, v56
	v_add_f32_e32 v57, 1.0, v57
	v_rcp_f32_e32 v56, v56
	v_rcp_f32_e32 v57, v57
	s_nop 0
	v_pk_mul_f32 v[52:53], v[52:53], v[56:57]
	s_nop 0
	v_pk_mul_f32 v[48:49], v[48:49], v[52:53]
	s_nop 0
	v_cvt_pk_bf16_f32 v48, v48, v49
	v_mul_f32_e32 v49, 0xbfb8aa3b, v54
	v_exp_f32_e32 v49, v49
	s_nop 0
	v_add_f32_e32 v49, 1.0, v49
	v_rcp_f32_e32 v52, v49
	v_mul_f32_e32 v49, 0xbfb8aa3b, v55
	v_exp_f32_e32 v49, v49
	s_nop 0
	v_add_f32_e32 v49, 1.0, v49
	v_rcp_f32_e32 v53, v49
	s_nop 0
	v_pk_mul_f32 v[52:53], v[54:55], v[52:53]
	s_nop 0
	v_pk_mul_f32 v[50:51], v[50:51], v[52:53]
	s_nop 0
	v_cvt_pk_bf16_f32 v49, v50, v51
	v_fmamk_f32 v50, v146, 0x3a000000, v194
	v_cmp_gt_f32_e32 vcc, s33, v50
	v_mul_f32_e32 v51, 0x4b800000, v50
	global_store_dwordx2 v[58:59], v[48:49], off offset:128
	v_cndmask_b32_e32 v50, v50, v51, vcc
	v_rsq_f32_e32 v50, v50
	v_mad_i64_i32 v[48:49], s[24:25], v147, s0, v[136:137]
	v_mul_f32_e32 v51, 0x45800000, v50
	v_cndmask_b32_e32 v50, v50, v51, vcc
	v_pk_mul_f32 v[44:45], v[44:45], v[50:51] op_sel_hi:[1,0]
	v_pk_mul_f32 v[46:47], v[46:47], v[50:51] op_sel_hi:[1,0]
	v_pk_mul_f32 v[42:43], v[42:43], v[50:51] op_sel_hi:[1,0]
	v_pk_mul_f32 v[40:41], v[40:41], v[50:51] op_sel_hi:[1,0]
	v_mul_f32_e32 v51, 0xbfb8aa3b, v44
	v_exp_f32_e32 v51, v51
	s_nop 0
	v_add_f32_e32 v51, 1.0, v51
	v_rcp_f32_e32 v52, v51
	v_mul_f32_e32 v51, 0xbfb8aa3b, v45
	v_exp_f32_e32 v51, v51
	s_nop 0
	v_add_f32_e32 v51, 1.0, v51
	v_rcp_f32_e32 v53, v51
	v_pk_mul_f32 v[36:37], v[36:37], v[50:51] op_sel_hi:[1,0]
	v_pk_mul_f32 v[32:33], v[32:33], v[50:51] op_sel_hi:[1,0]
	v_pk_mul_f32 v[38:39], v[38:39], v[50:51] op_sel_hi:[1,0]
	v_pk_mul_f32 v[44:45], v[44:45], v[52:53]
	v_pk_mul_f32 v[34:35], v[34:35], v[50:51] op_sel_hi:[1,0]
	v_pk_mul_f32 v[40:41], v[40:41], v[44:45]
	s_nop 0
	v_cvt_pk_bf16_f32 v40, v40, v41
	v_mul_f32_e32 v41, 0xbfb8aa3b, v46
	v_exp_f32_e32 v41, v41
	s_nop 0
	v_add_f32_e32 v41, 1.0, v41
	v_rcp_f32_e32 v44, v41
	v_mul_f32_e32 v41, 0xbfb8aa3b, v47
	v_exp_f32_e32 v41, v41
	s_nop 0
	v_add_f32_e32 v41, 1.0, v41
	v_rcp_f32_e32 v45, v41
	s_nop 0
	v_pk_mul_f32 v[44:45], v[46:47], v[44:45]
	s_nop 0
	v_pk_mul_f32 v[42:43], v[42:43], v[44:45]
	s_nop 0
	v_cvt_pk_bf16_f32 v41, v42, v43
	v_lshl_add_u64 v[42:43], v[48:49], 0, v[122:123]
	global_store_dwordx2 v[42:43], v[40:41], off
	v_mul_f32_e32 v40, 0xbfb8aa3b, v36
	v_mul_f32_e32 v41, 0xbfb8aa3b, v37
	v_exp_f32_e32 v40, v40
	v_exp_f32_e32 v41, v41
	v_add_f32_e32 v40, 1.0, v40
	v_add_f32_e32 v41, 1.0, v41
	v_rcp_f32_e32 v40, v40
	v_rcp_f32_e32 v41, v41
	s_nop 0
	v_pk_mul_f32 v[36:37], v[36:37], v[40:41]
	s_nop 0
	v_pk_mul_f32 v[32:33], v[32:33], v[36:37]
	s_nop 0
	v_cvt_pk_bf16_f32 v32, v32, v33
	v_mul_f32_e32 v33, 0xbfb8aa3b, v38
	v_exp_f32_e32 v33, v33
	s_nop 0
	v_add_f32_e32 v33, 1.0, v33
	v_rcp_f32_e32 v36, v33
	v_mul_f32_e32 v33, 0xbfb8aa3b, v39
	v_exp_f32_e32 v33, v33
	s_nop 0
	v_add_f32_e32 v33, 1.0, v33
	v_rcp_f32_e32 v37, v33
	s_nop 0
	v_pk_mul_f32 v[36:37], v[38:39], v[36:37]
	s_nop 0
	v_pk_mul_f32 v[34:35], v[34:35], v[36:37]
	s_nop 0
	v_cvt_pk_bf16_f32 v33, v34, v35
	v_fmamk_f32 v34, v144, 0x3a000000, v194
	v_cmp_gt_f32_e32 vcc, s33, v34
	v_mul_f32_e32 v35, 0x4b800000, v34
	global_store_dwordx2 v[42:43], v[32:33], off offset:128
	v_cndmask_b32_e32 v34, v34, v35, vcc
	v_rsq_f32_e32 v34, v34
	v_mad_i64_i32 v[32:33], s[24:25], v145, s0, v[136:137]
; __device__ __forceinline__ unsigned cvt_pk_bf16(float lo, float hi) { f32x2 v = {lo, hi}; bf16x2_t b = __builtin_convertvector(v, bf16x2_t); return __builtin_bit_cast(unsigned, b); }
; __device__ __forceinline__ float silu_(float z) { return z * sigmoid_(z); }
; #define PG8_BAR __builtin_amdgcn_s_barrier()
; template <class Epi, class Sched, bool ALIGN_EPI = false, bool SP2 = false>
; __device__ __forceinline__ void gemm_phase(PG8_LAS unsigned char* lds, const Gemm g, const Sched& S, const Epi& E) {
;     ...
;         if (!has_next) break;
; #pragma unroll
;         for (int a = 0; a < 2; ++a)
; #pragma unroll
;             for (int b = 0; b < 2; ++b)
; #pragma unroll
;                 for (int m = 0; m < 4; ++m)
; #pragma unroll
;                     for (int n = 0; n < 2; ++n) acc[a][b][m][n] = (f32x4){0.f, 0.f, 0.f, 0.f};
;         cur = nxt; cA = nA; cB = nB; ++ui;
;         if constexpr (ALIGN_EPI) { if (wr == 1) PG8_BAR; }
;     __device__ __forceinline__ void operator()(const f32x4 (&acc)[2][2][4][2], const Unit& u, int wr, int wc, int fr, int fq) const {
;     ...
;             for (int m = 0; m < 4; ++m) { bf16_t* rowp = H + (size_t)(row0 + ai * HALF + m * 16) * DFF;
;                 const float rs = rsqrtf(rsv[ai][m] * (1.f / DM) + EPS);
; #pragma unroll
;                 for (int bj = 0; bj < 2; ++bj) { const f32x4 a = acc[ai][bj][m][0] * rs, g = acc[ai][bj][m][1] * rs;
;                     const int col = 16 * (8 * u.pn + 4 * bj + wc) + 4 * fq;
;                     u32x2 w; w.x = cvt_pk_bf16(silu_(a[0]) * g[0], silu_(a[1]) * g[1]); w.y = cvt_pk_bf16(silu_(a[2]) * g[2], silu_(a[3]) * g[3]);
;                     *(u32x2*)(rowp + col) = w; } }
	v_mul_f32_e32 v35, 0x45800000, v34
	v_cndmask_b32_e32 v34, v34, v35, vcc
	v_pk_mul_f32 v[28:29], v[28:29], v[34:35] op_sel_hi:[1,0]
	v_pk_mul_f32 v[30:31], v[30:31], v[34:35] op_sel_hi:[1,0]
	v_pk_mul_f32 v[26:27], v[26:27], v[34:35] op_sel_hi:[1,0]
	v_pk_mul_f32 v[24:25], v[24:25], v[34:35] op_sel_hi:[1,0]
	v_mul_f32_e32 v35, 0xbfb8aa3b, v28
	v_exp_f32_e32 v35, v35
	s_nop 0
	v_add_f32_e32 v35, 1.0, v35
	v_rcp_f32_e32 v36, v35
	v_mul_f32_e32 v35, 0xbfb8aa3b, v29
	v_exp_f32_e32 v35, v35
	s_nop 0
	v_add_f32_e32 v35, 1.0, v35
	v_rcp_f32_e32 v37, v35
	v_pk_mul_f32 v[20:21], v[20:21], v[34:35] op_sel_hi:[1,0]
	v_pk_mul_f32 v[16:17], v[16:17], v[34:35] op_sel_hi:[1,0]
	v_pk_mul_f32 v[22:23], v[22:23], v[34:35] op_sel_hi:[1,0]
	v_pk_mul_f32 v[28:29], v[28:29], v[36:37]
	v_pk_mul_f32 v[18:19], v[18:19], v[34:35] op_sel_hi:[1,0]
	v_pk_mul_f32 v[24:25], v[24:25], v[28:29]
	s_nop 0
	v_cvt_pk_bf16_f32 v24, v24, v25
	v_mul_f32_e32 v25, 0xbfb8aa3b, v30
	v_exp_f32_e32 v25, v25
	s_nop 0
	v_add_f32_e32 v25, 1.0, v25
	v_rcp_f32_e32 v28, v25
	v_mul_f32_e32 v25, 0xbfb8aa3b, v31
	v_exp_f32_e32 v25, v25
	s_nop 0
	v_add_f32_e32 v25, 1.0, v25
	v_rcp_f32_e32 v29, v25
	s_nop 0
	v_pk_mul_f32 v[28:29], v[30:31], v[28:29]
	s_nop 0
	v_pk_mul_f32 v[26:27], v[26:27], v[28:29]
	s_nop 0
	v_cvt_pk_bf16_f32 v25, v26, v27
	v_lshl_add_u64 v[26:27], v[32:33], 0, v[122:123]
	global_store_dwordx2 v[26:27], v[24:25], off
	v_mul_f32_e32 v24, 0xbfb8aa3b, v20
	v_mul_f32_e32 v25, 0xbfb8aa3b, v21
	v_exp_f32_e32 v24, v24
	v_exp_f32_e32 v25, v25
	v_add_f32_e32 v24, 1.0, v24
	v_add_f32_e32 v25, 1.0, v25
	v_rcp_f32_e32 v24, v24
	v_rcp_f32_e32 v25, v25
	s_nop 0
	v_pk_mul_f32 v[20:21], v[20:21], v[24:25]
	s_nop 0
	v_pk_mul_f32 v[16:17], v[16:17], v[20:21]
	s_nop 0
	v_cvt_pk_bf16_f32 v16, v16, v17
	v_mul_f32_e32 v17, 0xbfb8aa3b, v22
	v_exp_f32_e32 v17, v17
	s_nop 0
	v_add_f32_e32 v17, 1.0, v17
	v_rcp_f32_e32 v20, v17
	v_mul_f32_e32 v17, 0xbfb8aa3b, v23
	v_exp_f32_e32 v17, v17
	s_nop 0
	v_add_f32_e32 v17, 1.0, v17
	v_rcp_f32_e32 v21, v17
	s_nop 0
	v_pk_mul_f32 v[20:21], v[22:23], v[20:21]
	s_nop 0
	v_pk_mul_f32 v[18:19], v[18:19], v[20:21]
	s_nop 0
	v_cvt_pk_bf16_f32 v17, v18, v19
	v_fmamk_f32 v18, v142, 0x3a000000, v194
	v_cmp_gt_f32_e32 vcc, s33, v18
	v_mul_f32_e32 v19, 0x4b800000, v18
	global_store_dwordx2 v[26:27], v[16:17], off offset:128
	v_cndmask_b32_e32 v18, v18, v19, vcc
	v_rsq_f32_e32 v18, v18
	v_mad_i64_i32 v[16:17], s[24:25], v143, s0, v[136:137]
	s_mov_b64 s[24:25], -1
	v_mul_f32_e32 v19, 0x45800000, v18
	v_cndmask_b32_e32 v18, v18, v19, vcc
	v_pk_mul_f32 v[12:13], v[12:13], v[18:19] op_sel_hi:[1,0]
	v_pk_mul_f32 v[14:15], v[14:15], v[18:19] op_sel_hi:[1,0]
	v_pk_mul_f32 v[10:11], v[10:11], v[18:19] op_sel_hi:[1,0]
	v_pk_mul_f32 v[8:9], v[8:9], v[18:19] op_sel_hi:[1,0]
	v_mul_f32_e32 v19, 0xbfb8aa3b, v12
	v_exp_f32_e32 v19, v19
	s_andn2_b64 vcc, exec, s[6:7]
	v_add_f32_e32 v19, 1.0, v19
	v_rcp_f32_e32 v20, v19
	v_mul_f32_e32 v19, 0xbfb8aa3b, v13
	v_exp_f32_e32 v19, v19
	s_nop 0
	v_add_f32_e32 v19, 1.0, v19
	v_rcp_f32_e32 v21, v19
	v_pk_mul_f32 v[4:5], v[4:5], v[18:19] op_sel_hi:[1,0]
	v_pk_mul_f32 v[0:1], v[0:1], v[18:19] op_sel_hi:[1,0]
	v_pk_mul_f32 v[6:7], v[6:7], v[18:19] op_sel_hi:[1,0]
	v_pk_mul_f32 v[12:13], v[12:13], v[20:21]
	v_pk_mul_f32 v[2:3], v[2:3], v[18:19] op_sel_hi:[1,0]
	v_pk_mul_f32 v[8:9], v[8:9], v[12:13]
	s_nop 0
	v_cvt_pk_bf16_f32 v8, v8, v9
	v_mul_f32_e32 v9, 0xbfb8aa3b, v14
	v_exp_f32_e32 v9, v9
	s_nop 0
	v_add_f32_e32 v9, 1.0, v9
	v_rcp_f32_e32 v12, v9
	v_mul_f32_e32 v9, 0xbfb8aa3b, v15
	v_exp_f32_e32 v9, v9
	s_nop 0
	v_add_f32_e32 v9, 1.0, v9
	v_rcp_f32_e32 v13, v9
	s_nop 0
	v_pk_mul_f32 v[12:13], v[14:15], v[12:13]
	s_nop 0
	v_pk_mul_f32 v[10:11], v[10:11], v[12:13]
	s_nop 0
	v_cvt_pk_bf16_f32 v9, v10, v11
	v_lshl_add_u64 v[10:11], v[16:17], 0, v[122:123]
	global_store_dwordx2 v[10:11], v[8:9], off
	v_mul_f32_e32 v8, 0xbfb8aa3b, v4
	v_mul_f32_e32 v9, 0xbfb8aa3b, v5
	v_exp_f32_e32 v8, v8
	v_exp_f32_e32 v9, v9
	v_add_f32_e32 v8, 1.0, v8
	v_add_f32_e32 v9, 1.0, v9
	v_rcp_f32_e32 v8, v8
	v_rcp_f32_e32 v9, v9
	s_nop 0
	v_pk_mul_f32 v[4:5], v[4:5], v[8:9]
	s_nop 0
	v_pk_mul_f32 v[0:1], v[0:1], v[4:5]
	s_nop 0
	v_cvt_pk_bf16_f32 v0, v0, v1
	v_mul_f32_e32 v1, 0xbfb8aa3b, v6
	v_exp_f32_e32 v1, v1
	s_nop 0
	v_add_f32_e32 v1, 1.0, v1
	v_rcp_f32_e32 v4, v1
	v_mul_f32_e32 v1, 0xbfb8aa3b, v7
	v_exp_f32_e32 v1, v1
	s_nop 0
	v_add_f32_e32 v1, 1.0, v1
	v_rcp_f32_e32 v5, v1
	s_nop 0
	v_pk_mul_f32 v[4:5], v[6:7], v[4:5]
	s_nop 0
	v_pk_mul_f32 v[2:3], v[2:3], v[4:5]
	s_nop 0
	v_cvt_pk_bf16_f32 v1, v2, v3
	global_store_dwordx2 v[10:11], v[0:1], off offset:128
	s_cbranch_vccnz .LBB0_718
	s_andn2_b64 vcc, exec, s[8:9]
	s_cbranch_vccnz .LBB0_717
	s_barrier
	s_branch .LBB0_717

; __device__ __forceinline__ int opaque_tid() { int t = threadIdx.x; asm volatile("" : "+v"(t)); return t; }
; __device__ __forceinline__ void rmsnorm_rows_bf16_to_f32(const bf16_t* src, const float* gain, float* dst) {
;     const int tid = opaque_tid(), lane = tid & 63, gw = blockIdx.x * 8 + (tid >> 6), ngw = gridDim.x * 8;
;     for (int m = gw; m < M; m += ngw) {
;         const bf16x8* xr = (const bf16x8*)(src + (size_t)m * DM) + lane;
;         float v[4][8]; float s = 0.f;
; #pragma unroll
;         for (int j = 0; j < 4; ++j) { unpack8(xr[64 * j], v[j]);
; #pragma unroll
;             for (int e = 0; e < 8; ++e) s += v[j][e] * v[j][e]; }
;         const float rstd = rsqrtf(wave_sum(s) * (1.f / DM) + EPS);
.LBB0_858:
	v_readlane_b32 s0, v253, 29
	v_ashrrev_i32_e32 v0, 6, v195
	s_nop 0
	v_add_u32_e32 v0, s0, v0
	s_mov_b32 s0, 0x8000
	v_cmp_gt_i32_e32 vcc, s0, v0
	s_and_saveexec_b64 s[0:1], vcc
	v_readlane_b32 s8, v253, 30
	v_readlane_b32 s9, v253, 31
	s_cbranch_execz .LBB0_861
	v_and_b32_e32 v1, 64, v237
	v_add_u32_e32 v1, 64, v1
	v_xor_b32_e32 v2, 1, v237
	v_cmp_lt_i32_e32 vcc, v2, v1
	v_and_b32_e32 v18, 63, v195
	v_lshlrev_b32_e32 v10, 5, v18
	v_cndmask_b32_e32 v2, v237, v2, vcc
	v_lshlrev_b32_e32 v12, 2, v2
	v_xor_b32_e32 v2, 2, v237
	v_cmp_lt_i32_e32 vcc, v2, v1
	v_readlane_b32 s0, v253, 0
	v_mov_b32_e32 v11, 0
	v_cndmask_b32_e32 v2, v237, v2, vcc
	v_lshlrev_b32_e32 v13, 2, v2
	v_xor_b32_e32 v2, 4, v237
	v_cmp_lt_i32_e32 vcc, v2, v1
	v_readlane_b32 s1, v253, 1
	v_readlane_b32 s2, v253, 2
	v_cndmask_b32_e32 v2, v237, v2, vcc
	v_lshlrev_b32_e32 v14, 2, v2
	v_xor_b32_e32 v2, 8, v237
	v_cmp_lt_i32_e32 vcc, v2, v1
	v_readlane_b32 s3, v253, 3
	v_readlane_b32 s4, v253, 4
	v_cndmask_b32_e32 v2, v237, v2, vcc
	v_lshlrev_b32_e32 v15, 2, v2
	v_xor_b32_e32 v2, 16, v237
	v_cmp_lt_i32_e32 vcc, v2, v1
	v_readlane_b32 s5, v253, 5
	v_readlane_b32 s6, v253, 6
	v_cndmask_b32_e32 v2, v237, v2, vcc
	v_lshlrev_b32_e32 v16, 2, v2
	v_xor_b32_e32 v2, 32, v237
	v_cmp_lt_i32_e32 vcc, v2, v1
	v_readlane_b32 s7, v253, 7
	v_or_b32_e32 v4, 0x1000, v10
	v_cndmask_b32_e32 v1, v237, v2, vcc
	v_lshlrev_b32_e32 v17, 2, v1
	v_ashrrev_i32_e32 v1, 31, v0
	v_lshlrev_b64 v[8:9], 12, v[0:1]
	v_lshl_or_b32 v8, v18, 4, v8
	v_lshlrev_b64 v[18:19], 13, v[0:1]
	v_or_b32_e32 v18, v18, v10
	v_lshl_add_u64 v[2:3], s[4:5], 0, v[10:11]
	v_mov_b32_e32 v5, v11
	v_or_b32_e32 v6, 0x1800, v10
	v_mov_b32_e32 v7, v11
	v_lshl_add_u64 v[8:9], s[68:69], 0, v[8:9]
	s_mov_b64 s[0:1], 0x6300000
	s_ashr_i32 s9, s8, 31
	v_lshl_add_u64 v[10:11], s[6:7], 0, v[18:19]
	s_mov_b64 s[2:3], 0x1000
	v_lshl_add_u64 v[4:5], s[4:5], 0, v[4:5]
	v_lshl_add_u64 v[6:7], s[4:5], 0, v[6:7]
	v_lshl_add_u64 v[8:9], v[8:9], 0, s[0:1]
	s_lshl_b64 s[0:1], s[8:9], 12
	v_lshl_add_u64 v[10:11], v[10:11], 0, s[2:3]
	s_lshl_b64 s[2:3], s[8:9], 13
	s_mov_b64 s[4:5], 0
	v_mov_b32_e32 v1, 0x358637bd
	s_mov_b32 s6, 0x800000
	s_movk_i32 s7, 0x7fff
	global_load_dwordx4 v[200:203], v[2:3], off offset:16
	global_load_dwordx4 v[204:207], v[2:3], off
	global_load_dwordx4 v[208:211], v[2:3], off offset:2048
	global_load_dwordx4 v[212:215], v[2:3], off offset:2064
	global_load_dwordx4 v[216:219], v[4:5], off
	global_load_dwordx4 v[220:223], v[4:5], off offset:16
	global_load_dwordx4 v[224:227], v[6:7], off
	global_load_dwordx4 v[228:231], v[6:7], off offset:16
	global_load_dwordx4 v[184:187], v[8:9], off
	global_load_dwordx4 v[188:191], v[8:9], off offset:1024
	global_load_dwordx4 v[192:195], v[8:9], off offset:2048
	global_load_dwordx4 v[196:199], v[8:9], off offset:3072
	v_lshl_add_u64 v[8:9], v[8:9], 0, s[0:1]
	s_waitcnt vmcnt(0) lgkmcnt(0)
.LBB0_860:
	s_waitcnt vmcnt(8)
	v_mov_b32_e32 v18, v184
	v_mov_b32_e32 v19, v185
	v_mov_b32_e32 v20, v186
	v_mov_b32_e32 v21, v187
	v_mov_b32_e32 v22, v188
	v_mov_b32_e32 v23, v189
	v_mov_b32_e32 v24, v190
	v_mov_b32_e32 v25, v191
	v_mov_b32_e32 v26, v192
	v_mov_b32_e32 v27, v193
	v_mov_b32_e32 v28, v194
	v_mov_b32_e32 v29, v195
	v_mov_b32_e32 v30, v196
	v_mov_b32_e32 v31, v197
	v_mov_b32_e32 v32, v198
	v_mov_b32_e32 v33, v199
	global_load_dwordx4 v[184:187], v[8:9], off
	global_load_dwordx4 v[188:191], v[8:9], off offset:1024
	global_load_dwordx4 v[192:195], v[8:9], off offset:2048
	global_load_dwordx4 v[196:199], v[8:9], off offset:3072
	v_mov_b32_e32 v34, v200
	v_mov_b32_e32 v35, v201
	v_mov_b32_e32 v36, v202
	v_mov_b32_e32 v37, v203
	v_mov_b32_e32 v38, v204
	v_mov_b32_e32 v39, v205
	v_mov_b32_e32 v40, v206
	v_mov_b32_e32 v41, v207
	v_add_u32_e32 v0, s8, v0
	v_lshl_add_u64 v[8:9], v[8:9], 0, s[0:1]
	v_and_b32_e32 v43, 0xffff0000, v20
	v_lshlrev_b32_e32 v42, 16, v20
	v_and_b32_e32 v45, 0xffff0000, v21
	v_lshlrev_b32_e32 v44, 16, v21
	v_and_b32_e32 v21, 0xffff0000, v18
	v_lshlrev_b32_e32 v20, 16, v18
	v_and_b32_e32 v47, 0xffff0000, v19
	v_lshlrev_b32_e32 v46, 16, v19
	v_and_b32_e32 v49, 0xffff0000, v24
	v_lshlrev_b32_e32 v48, 16, v24
	v_and_b32_e32 v51, 0xffff0000, v25
	v_lshlrev_b32_e32 v50, 16, v25
	v_pk_mul_f32 v[24:25], v[20:21], v[20:21]
	v_and_b32_e32 v57, 0xffff0000, v28
	v_lshlrev_b32_e32 v56, 16, v28
	v_and_b32_e32 v59, 0xffff0000, v29
	v_lshlrev_b32_e32 v58, 16, v29
	v_and_b32_e32 v29, 0xffff0000, v26
	v_lshlrev_b32_e32 v28, 16, v26
	v_and_b32_e32 v61, 0xffff0000, v27
	v_lshlrev_b32_e32 v60, 16, v27
	v_and_b32_e32 v27, 0xffff0000, v32
	v_lshlrev_b32_e32 v26, 16, v32
	v_and_b32_e32 v63, 0xffff0000, v33
	v_lshlrev_b32_e32 v62, 16, v33
	v_and_b32_e32 v33, 0xffff0000, v30
	v_lshlrev_b32_e32 v32, 16, v30
	v_and_b32_e32 v65, 0xffff0000, v31
	v_lshlrev_b32_e32 v64, 16, v31
	v_pk_mul_f32 v[30:31], v[46:47], v[46:47]
	v_add_f32_e32 v24, v24, v25
	v_add_f32_e32 v24, v30, v24
	v_pk_mul_f32 v[18:19], v[42:43], v[42:43]
	v_add_f32_e32 v24, v31, v24
	v_add_f32_e32 v18, v18, v24
	v_and_b32_e32 v53, 0xffff0000, v22
	v_lshlrev_b32_e32 v52, 16, v22
	v_and_b32_e32 v55, 0xffff0000, v23
	v_lshlrev_b32_e32 v54, 16, v23
	v_pk_mul_f32 v[22:23], v[44:45], v[44:45]
	v_add_f32_e32 v18, v19, v18
	v_add_f32_e32 v18, v22, v18
	v_pk_mul_f32 v[70:71], v[52:53], v[52:53]
	v_add_f32_e32 v18, v23, v18
	v_add_f32_e32 v18, v70, v18
	v_pk_mul_f32 v[72:73], v[54:55], v[54:55]
	v_add_f32_e32 v18, v71, v18
	v_add_f32_e32 v18, v72, v18
	v_pk_mul_f32 v[66:67], v[48:49], v[48:49]
	v_add_f32_e32 v18, v73, v18
	v_add_f32_e32 v18, v66, v18
	v_pk_mul_f32 v[68:69], v[50:51], v[50:51]
	v_add_f32_e32 v18, v67, v18
	v_add_f32_e32 v18, v68, v18
	v_pk_mul_f32 v[78:79], v[28:29], v[28:29]
	v_add_f32_e32 v18, v69, v18
	v_add_f32_e32 v18, v78, v18
	v_pk_mul_f32 v[80:81], v[60:61], v[60:61]
	v_add_f32_e32 v18, v79, v18
	v_add_f32_e32 v18, v80, v18
	v_pk_mul_f32 v[74:75], v[56:57], v[56:57]
	v_add_f32_e32 v18, v81, v18
	v_add_f32_e32 v18, v74, v18
	v_pk_mul_f32 v[76:77], v[58:59], v[58:59]
	v_add_f32_e32 v18, v75, v18
	v_add_f32_e32 v18, v76, v18
	v_pk_mul_f32 v[86:87], v[32:33], v[32:33]
	v_add_f32_e32 v18, v77, v18
	v_add_f32_e32 v18, v86, v18
	v_pk_mul_f32 v[88:89], v[64:65], v[64:65]
	v_add_f32_e32 v18, v87, v18
	v_add_f32_e32 v18, v88, v18
	v_pk_mul_f32 v[82:83], v[26:27], v[26:27]
	v_add_f32_e32 v18, v89, v18
	v_add_f32_e32 v18, v82, v18
	v_pk_mul_f32 v[84:85], v[62:63], v[62:63]
	v_add_f32_e32 v18, v83, v18
	v_add_f32_e32 v18, v84, v18
	v_add_f32_e32 v18, v85, v18
	ds_bpermute_b32 v19, v12, v18
	s_waitcnt lgkmcnt(0)
; __device__ __forceinline__ void rmsnorm_rows_bf16_to_f32(const bf16_t* src, const float* gain, float* dst) {
;     ...
;         const float rstd = rsqrtf(wave_sum(s) * (1.f / DM) + EPS);
; #pragma unroll
;         for (int j = 0; j < 4; ++j) { const int c = (lane + 64 * j) * 8; const f32x4 g0 = *(const f32x4*)(gain + c), g1 = *(const f32x4*)(gain + c + 4);
;             f32x4 o0 = {v[j][0] * rstd * g0[0], v[j][1] * rstd * g0[1], v[j][2] * rstd * g0[2], v[j][3] * rstd * g0[3]};
;             f32x4 o1 = {v[j][4] * rstd * g1[0], v[j][5] * rstd * g1[1], v[j][6] * rstd * g1[2], v[j][7] * rstd * g1[3]};
;             *(f32x4*)(dst + (size_t)m * DM + c) = o0; *(f32x4*)(dst + (size_t)m * DM + c + 4) = o1; }
;     }
	v_add_f32_e32 v18, v18, v19
	ds_bpermute_b32 v19, v13, v18
	s_waitcnt lgkmcnt(0)
	v_add_f32_e32 v18, v18, v19
	ds_bpermute_b32 v19, v14, v18
	s_waitcnt lgkmcnt(0)
	v_add_f32_e32 v18, v18, v19
	ds_bpermute_b32 v19, v15, v18
	s_waitcnt lgkmcnt(0)
	v_add_f32_e32 v18, v18, v19
	ds_bpermute_b32 v19, v16, v18
	s_waitcnt lgkmcnt(0)
	v_add_f32_e32 v18, v18, v19
	ds_bpermute_b32 v19, v17, v18
	s_waitcnt lgkmcnt(0)
	v_add_f32_e32 v18, v18, v19
	v_fmamk_f32 v18, v18, 0x3a000000, v1
	v_mul_f32_e32 v19, 0x4b800000, v18
	v_cmp_gt_f32_e32 vcc, s6, v18
	s_nop 1
	v_cndmask_b32_e32 v18, v18, v19, vcc
	v_rsq_f32_e32 v18, v18
	s_nop 0
	v_mul_f32_e32 v19, 0x45800000, v18
	v_cndmask_b32_e32 v30, v18, v19, vcc
	v_pk_mul_f32 v[18:19], v[30:31], v[20:21] op_sel_hi:[0,1]
	v_pk_mul_f32 v[20:21], v[30:31], v[46:47] op_sel_hi:[0,1]
	v_pk_mul_f32 v[22:23], v[30:31], v[42:43] op_sel_hi:[0,1]
	v_pk_mul_f32 v[24:25], v[30:31], v[44:45] op_sel_hi:[0,1]
	v_pk_mul_f32 v[20:21], v[40:41], v[20:21]
	v_pk_mul_f32 v[18:19], v[38:39], v[18:19]
	v_pk_mul_f32 v[24:25], v[36:37], v[24:25]
	v_pk_mul_f32 v[22:23], v[34:35], v[22:23]
	global_store_dwordx4 v[10:11], v[18:21], off offset:-4096
	global_store_dwordx4 v[10:11], v[22:25], off offset:-4080
	s_nop 1
	v_mov_b32_e32 v18, v208
	v_mov_b32_e32 v19, v209
	v_mov_b32_e32 v20, v210
	v_mov_b32_e32 v21, v211
	v_mov_b32_e32 v22, v212
	v_mov_b32_e32 v23, v213
	v_mov_b32_e32 v24, v214
	v_mov_b32_e32 v25, v215
	v_pk_mul_f32 v[34:35], v[30:31], v[54:55] op_sel_hi:[0,1]
	v_pk_mul_f32 v[36:37], v[30:31], v[52:53] op_sel_hi:[0,1]
	v_pk_mul_f32 v[38:39], v[30:31], v[50:51] op_sel_hi:[0,1]
	v_pk_mul_f32 v[40:41], v[30:31], v[48:49] op_sel_hi:[0,1]
	v_pk_mul_f32 v[28:29], v[30:31], v[28:29] op_sel_hi:[0,1]
	v_pk_mul_f32 v[32:33], v[30:31], v[32:33] op_sel_hi:[0,1]
	v_cmp_lt_i32_e32 vcc, s7, v0
	v_pk_mul_f32 v[26:27], v[30:31], v[26:27] op_sel_hi:[0,1]
	s_or_b64 s[4:5], vcc, s[4:5]
	v_pk_mul_f32 v[18:19], v[18:19], v[36:37]
	v_pk_mul_f32 v[20:21], v[20:21], v[34:35]
	v_pk_mul_f32 v[22:23], v[22:23], v[40:41]
	v_pk_mul_f32 v[24:25], v[24:25], v[38:39]
	global_store_dwordx4 v[10:11], v[18:21], off offset:-2048
	global_store_dwordx4 v[10:11], v[22:25], off offset:-2032
	s_nop 1
	v_mov_b32_e32 v18, v216
	v_mov_b32_e32 v19, v217
	v_mov_b32_e32 v20, v218
	v_mov_b32_e32 v21, v219
	v_mov_b32_e32 v22, v220
	v_mov_b32_e32 v23, v221
	v_mov_b32_e32 v24, v222
	v_mov_b32_e32 v25, v223
	v_pk_mul_f32 v[34:35], v[30:31], v[60:61] op_sel_hi:[0,1]
	v_pk_mul_f32 v[36:37], v[30:31], v[58:59] op_sel_hi:[0,1]
	v_pk_mul_f32 v[38:39], v[30:31], v[56:57] op_sel_hi:[0,1]
	v_pk_mul_f32 v[18:19], v[18:19], v[28:29]
	v_pk_mul_f32 v[20:21], v[20:21], v[34:35]
	v_pk_mul_f32 v[22:23], v[22:23], v[38:39]
	v_pk_mul_f32 v[24:25], v[24:25], v[36:37]
	global_store_dwordx4 v[10:11], v[18:21], off
	global_store_dwordx4 v[10:11], v[22:25], off offset:16
	s_nop 1
	v_mov_b32_e32 v18, v224
	v_mov_b32_e32 v19, v225
	v_mov_b32_e32 v20, v226
	v_mov_b32_e32 v21, v227
	v_mov_b32_e32 v22, v228
	v_mov_b32_e32 v23, v229
	v_mov_b32_e32 v24, v230
	v_mov_b32_e32 v25, v231
	v_pk_mul_f32 v[28:29], v[30:31], v[64:65] op_sel_hi:[0,1]
	v_pk_mul_f32 v[34:35], v[30:31], v[62:63] op_sel_hi:[0,1]
	v_pk_mul_f32 v[18:19], v[18:19], v[32:33]
	v_pk_mul_f32 v[20:21], v[20:21], v[28:29]
	v_pk_mul_f32 v[22:23], v[22:23], v[26:27]
	v_pk_mul_f32 v[24:25], v[24:25], v[34:35]
	global_store_dwordx4 v[10:11], v[18:21], off offset:2048
	global_store_dwordx4 v[10:11], v[22:25], off offset:2064
	v_lshl_add_u64 v[10:11], v[10:11], 0, s[2:3]
	s_andn2_b64 exec, exec, s[4:5]
	s_cbranch_execnz .LBB0_860
.LBB0_861:
	s_waitcnt vmcnt(0)
	s_endpgm
